# bundle + K-loop barrier slid before the last MFMA of each compute segment
# speedup vs baseline: 1.0038x; 1.0038x over previous
;     __device__ __forceinline__ const char* tile(const Unit& u, int t) const { return A + (size_t)u.pm * 2 * hstep() + (size_t)t * (BK * 2); }
;     __device__ __forceinline__ const char* tile(const Unit& u, int t) const { return U + (long)(t >> 2) * xoff + (size_t)u.pn * (1024 * 512) + (size_t)u.pm * 2 * hstep() + (size_t)(t & 3) * (BK * 2); }
; #define PG8_STAGE(bufoff, gbase, voff) do { _Pragma("unroll") for (int _i = 0; _i < 2; ++_i) \
;         __builtin_amdgcn_global_load_lds((const unsigned*)((const char*)(gbase) + (voff)[_i]), (PG8_LAS unsigned*)(lds + (bufoff) + ldsw + _i * 8192), 16, 0, 0); } while (0)
; #define PG8_LDA(dst, b, h) do { _Pragma("unroll") for (int m = 0; m < 4; ++m) _Pragma("unroll") for (int k = 0; k < 2; ++k) dst[m][k] = *(const PG8_LAS bf16x8*)(lds + PG8_SA(b, h) + aoff + m * 2048 + k * 1024); } while (0)
; #define PG8_WAIT_V(n) asm volatile("s_waitcnt vmcnt(" #n ")" ::: "memory")
; #define PG8_BAR __builtin_amdgcn_s_barrier()
;     ...
;         for (int t = 0; t < nt; t += 2) {
;             const bool last = (t == nt - 2);
;             const char* a1 = AS.tile(cur, t + 1);
;             const char* a2 = last ? AS.tile(nu, 0) : AS.tile(cur, t + 2); const char* b2 = last ? nB : cB + (size_t)(t + 2) * kstep;
;             const char* a3 = last ? AS.tile(nu, 1) : AS.tile(cur, t + 3); const char* b3 = b2 + kstep;
;             PG8_LDB(B0, 0, 0); PG8_LDB(B1, 0, 1); PG8_SCHED; PG8_LDA(At, 0, 0); PG8_STAGE(PG8_SA(1, 1), a1 + hstepA, voffA);
;             PG8_WAIT_V(8); PG8_WAIT_L(0); PG8_BAR; PG8_MMA(0, 0, At, B0); PG8_MMA(0, 1, At, B1); PG8_BAR; PG8_SCHED;
;             PG8_LDA(At, 0, 1); PG8_STAGE(PG8_SB(0, 0), b2, voffB); PG8_STAGE(PG8_SB(0, 1), b2 + hstepB, voffB); PG8_STAGE(PG8_SA(0, 0), a2, voffA);
;             PG8_WAIT_V(8); PG8_WAIT_L(0); PG8_BAR; PG8_MMA(1, 0, At, B0); PG8_MMA(1, 1, At, B1); PG8_BAR; PG8_SCHED;
;             PG8_LDB(B0, 1, 0); PG8_LDB(B1, 1, 1); PG8_SCHED; PG8_LDA(At, 1, 0); PG8_STAGE(PG8_SA(0, 1), a2 + hstepA, voffA);
;             PG8_WAIT_V(8); PG8_WAIT_L(0); PG8_BAR; PG8_MMA(0, 0, At, B0); PG8_MMA(0, 1, At, B1); PG8_BAR; PG8_SCHED;
;             PG8_LDA(At, 1, 1); PG8_STAGE(PG8_SB(1, 0), b3, voffB); PG8_STAGE(PG8_SB(1, 1), b3 + hstepB, voffB); PG8_STAGE(PG8_SA(1, 0), a3, voffA);
;             PG8_WAIT_V(8); PG8_WAIT_L(0); PG8_BAR; PG8_MMA(1, 0, At, B0); PG8_MMA(1, 1, At, B1); PG8_BAR; PG8_SCHED;
.Lpeel_380:
	s_add_u32 s28, s1, s2
	s_addc_u32 s29, s77, s3
	s_add_u32 s48, s28, 0x100
	s_addc_u32 s49, s29, 0
	s_add_u32 s46, s82, s2
	s_addc_u32 s47, s83, s3
	s_add_u32 s28, s28, 0x180
	s_addc_u32 s29, s29, 0
	s_add_i32 s85, 0, 0x10000
	s_add_i32 s88, 0, 0x14000
	v_add_u32_e32 v158, s85, v174
	v_add_u32_e32 v186, s88, v174
	ds_read_b128 v[132:135], v158
	ds_read_b128 v[136:139], v158 offset:1024
	ds_read_b128 v[140:143], v158 offset:2048
	ds_read_b128 v[158:161], v158 offset:3072
	ds_read_b128 v[162:165], v186
	ds_read_b128 v[166:169], v186 offset:1024
	ds_read_b128 v[182:185], v186 offset:2048
	ds_read_b128 v[186:189], v186 offset:3072
	s_cmpk_eq_i32 s2, 0x700
	s_cselect_b32 s29, s81, s29
	s_cselect_b32 s28, s80, s28
	s_cselect_b32 s47, s76, s47
	s_cselect_b32 s46, s75, s46
	s_cselect_b32 s49, s79, s49
	s_cselect_b32 s48, s78, s48
	v_lshl_add_u64 v[222:223], v[128:129], 0, s[2:3]
	s_add_i32 m0, s27, 0xc000
	ds_read_b128 v[190:193], v180
	ds_read_b128 v[194:197], v180 offset:1024
	ds_read_b128 v[198:201], v180 offset:2048
	ds_read_b128 v[204:207], v180 offset:3072
	ds_read_b128 v[218:221], v180 offset:4096
	ds_read_b128 v[238:241], v180 offset:5120
	ds_read_b128 v[242:245], v180 offset:6144
	ds_read_b128 v[246:249], v180 offset:7168
	global_load_lds_dwordx4 v[222:223], off
	v_lshl_add_u64 v[222:223], v[130:131], 0, s[2:3]
	s_add_i32 m0, s27, 0xe000
	s_nop 0
	global_load_lds_dwordx4 v[222:223], off
	s_waitcnt vmcnt(8)
	s_waitcnt lgkmcnt(0)
	s_barrier
	s_setprio 1
	s_waitcnt lgkmcnt(0)
	v_mfma_f32_16x16x32_bf16 v[124:127], v[132:135], v[190:193], 0
	v_mfma_f32_16x16x32_bf16 v[120:123], v[140:143], v[190:193], 0
	v_mfma_f32_16x16x32_bf16 v[108:111], v[132:135], v[198:201], 0
	v_mfma_f32_16x16x32_bf16 v[104:107], v[140:143], v[198:201], 0
	v_mfma_f32_16x16x32_bf16 v[92:95], v[132:135], v[218:221], 0
	v_mfma_f32_16x16x32_bf16 v[88:91], v[140:143], v[218:221], 0
	v_mfma_f32_16x16x32_bf16 v[76:79], v[132:135], v[242:245], 0
	v_mfma_f32_16x16x32_bf16 v[72:75], v[140:143], v[242:245], 0
	v_mfma_f32_16x16x32_bf16 v[124:127], v[136:139], v[194:197], v[124:127]
	v_mfma_f32_16x16x32_bf16 v[120:123], v[158:161], v[194:197], v[120:123]
	v_mfma_f32_16x16x32_bf16 v[108:111], v[136:139], v[204:207], v[108:111]
	v_mfma_f32_16x16x32_bf16 v[104:107], v[158:161], v[204:207], v[104:107]
	v_mfma_f32_16x16x32_bf16 v[92:95], v[136:139], v[238:241], v[92:95]
	v_mfma_f32_16x16x32_bf16 v[88:91], v[158:161], v[238:241], v[88:91]
	v_mfma_f32_16x16x32_bf16 v[76:79], v[136:139], v[246:249], v[76:79]
	v_mfma_f32_16x16x32_bf16 v[72:75], v[158:161], v[246:249], v[72:75]
	s_setprio 0
	s_setprio 1
	v_mfma_f32_16x16x32_bf16 v[116:119], v[162:165], v[190:193], 0
	v_mfma_f32_16x16x32_bf16 v[112:115], v[182:185], v[190:193], 0
	v_mfma_f32_16x16x32_bf16 v[100:103], v[162:165], v[198:201], 0
	v_mfma_f32_16x16x32_bf16 v[96:99], v[182:185], v[198:201], 0
	v_mfma_f32_16x16x32_bf16 v[84:87], v[162:165], v[218:221], 0
	v_mfma_f32_16x16x32_bf16 v[80:83], v[182:185], v[218:221], 0
	v_mfma_f32_16x16x32_bf16 v[68:71], v[162:165], v[242:245], 0
	v_mfma_f32_16x16x32_bf16 v[64:67], v[182:185], v[242:245], 0
	v_mfma_f32_16x16x32_bf16 v[116:119], v[166:169], v[194:197], v[116:119]
	v_mfma_f32_16x16x32_bf16 v[112:115], v[186:189], v[194:197], v[112:115]
	v_mfma_f32_16x16x32_bf16 v[100:103], v[166:169], v[204:207], v[100:103]
	v_mfma_f32_16x16x32_bf16 v[96:99], v[186:189], v[204:207], v[96:99]
	v_mfma_f32_16x16x32_bf16 v[84:87], v[166:169], v[238:241], v[84:87]
	v_mfma_f32_16x16x32_bf16 v[80:83], v[186:189], v[238:241], v[80:83]
	v_mfma_f32_16x16x32_bf16 v[68:71], v[166:169], v[246:249], v[68:71]
	s_barrier
	v_mfma_f32_16x16x32_bf16 v[64:67], v[186:189], v[246:249], v[64:67]
	s_setprio 0
	s_add_i32 s85, s85, s52
	v_lshl_add_u64 v[222:223], s[46:47], 0, v[146:147]
	s_mov_b32 m0, s85
	ds_read_b128 v[190:193], v180 offset:16384
	ds_read_b128 v[194:197], v180 offset:17408
	ds_read_b128 v[198:201], v180 offset:18432
	ds_read_b128 v[204:207], v180 offset:19456
	ds_read_b128 v[218:221], v180 offset:20480
	ds_read_b128 v[238:241], v180 offset:21504
	ds_read_b128 v[242:245], v180 offset:22528
	ds_read_b128 v[246:249], v180 offset:23552
	global_load_lds_dwordx4 v[222:223], off
	s_add_i32 m0, s85, 0x2000
	s_add_u32 s86, s46, 0x40000
	v_lshl_add_u64 v[224:225], s[46:47], 0, v[150:151]
	s_addc_u32 s87, s47, 0
	s_add_i32 s85, s88, s52
	global_load_lds_dwordx4 v[224:225], off
	v_lshl_add_u64 v[250:251], s[86:87], 0, v[146:147]
	s_mov_b32 m0, s85
	s_nop 0
	global_load_lds_dwordx4 v[250:251], off
	v_lshl_add_u64 v[250:251], s[86:87], 0, v[150:151]
	s_add_i32 m0, s85, 0x2000
	s_nop 0
	global_load_lds_dwordx4 v[250:251], off
	v_lshl_add_u64 v[250:251], s[48:49], 0, v[144:145]
	s_mov_b32 m0, s27
	s_nop 0
	global_load_lds_dwordx4 v[250:251], off
	v_lshl_add_u64 v[250:251], s[48:49], 0, v[148:149]
	s_mov_b32 m0, s57
	s_nop 0
	global_load_lds_dwordx4 v[250:251], off
	s_waitcnt vmcnt(8)
	s_waitcnt lgkmcnt(0)
	s_barrier
; #define PG8_STAGE(bufoff, gbase, voff) do { _Pragma("unroll") for (int _i = 0; _i < 2; ++_i) \
;         __builtin_amdgcn_global_load_lds((const unsigned*)((const char*)(gbase) + (voff)[_i]), (PG8_LAS unsigned*)(lds + (bufoff) + ldsw + _i * 8192), 16, 0, 0); } while (0)
; #define PG8_LDA(dst, b, h) do { _Pragma("unroll") for (int m = 0; m < 4; ++m) _Pragma("unroll") for (int k = 0; k < 2; ++k) dst[m][k] = *(const PG8_LAS bf16x8*)(lds + PG8_SA(b, h) + aoff + m * 2048 + k * 1024); } while (0)
; #define PG8_LDB(dst, b, h) do { _Pragma("unroll") for (int n = 0; n < 2; ++n) _Pragma("unroll") for (int k = 0; k < 2; ++k) dst[n][k] = *(const PG8_LAS bf16x8*)(lds + PG8_SB(b, h) + boff + n * 2048 + k * 1024); } while (0)
; #define PG8_MMA(ai, bj, At, Bt) do { __builtin_amdgcn_s_setprio(1); _Pragma("unroll") for (int m = 0; m < 4; ++m) _Pragma("unroll") for (int n = 0; n < 2; ++n) _Pragma("unroll") for (int k = 0; k < 2; ++k) \
;         acc[ai][bj][m][n] = __builtin_amdgcn_mfma_f32_16x16x32_bf16(Bt[n][k], At[m][k], acc[ai][bj][m][n], 0, 0, 0); __builtin_amdgcn_s_setprio(0); } while (0)
; #define PG8_WAIT_V(n) asm volatile("s_waitcnt vmcnt(" #n ")" ::: "memory")
; #define PG8_WAIT_L(n) asm volatile("s_waitcnt lgkmcnt(" #n ")" ::: "memory")
; #define PG8_BAR __builtin_amdgcn_s_barrier()
; #define PG8_SCHED __builtin_amdgcn_sched_barrier(0)
;     ...
;             PG8_WAIT_V(8); PG8_WAIT_L(0); PG8_BAR; PG8_MMA(0, 0, At, B0); PG8_MMA(0, 1, At, B1); PG8_BAR; PG8_SCHED;
;             PG8_LDA(At, 0, 1); PG8_STAGE(PG8_SB(0, 0), b2, voffB); PG8_STAGE(PG8_SB(0, 1), b2 + hstepB, voffB); PG8_STAGE(PG8_SA(0, 0), a2, voffA);
;             PG8_WAIT_V(8); PG8_WAIT_L(0); PG8_BAR; PG8_MMA(1, 0, At, B0); PG8_MMA(1, 1, At, B1); PG8_BAR; PG8_SCHED;
;             PG8_LDB(B0, 1, 0); PG8_LDB(B1, 1, 1); PG8_SCHED; PG8_LDA(At, 1, 0); PG8_STAGE(PG8_SA(0, 1), a2 + hstepA, voffA);
;             PG8_WAIT_V(8); PG8_WAIT_L(0); PG8_BAR; PG8_MMA(0, 0, At, B0); PG8_MMA(0, 1, At, B1); PG8_BAR; PG8_SCHED;
;             PG8_LDA(At, 1, 1); PG8_STAGE(PG8_SB(1, 0), b3, voffB); PG8_STAGE(PG8_SB(1, 1), b3 + hstepB, voffB); PG8_STAGE(PG8_SA(1, 0), a3, voffA);
	s_setprio 1
	s_waitcnt lgkmcnt(0)
	v_mfma_f32_16x16x32_bf16 v[60:63], v[132:135], v[190:193], 0
	v_mfma_f32_16x16x32_bf16 v[56:59], v[140:143], v[190:193], 0
	v_mfma_f32_16x16x32_bf16 v[44:47], v[132:135], v[198:201], 0
	v_mfma_f32_16x16x32_bf16 v[40:43], v[140:143], v[198:201], 0
	v_mfma_f32_16x16x32_bf16 v[28:31], v[132:135], v[218:221], 0
	v_mfma_f32_16x16x32_bf16 v[24:27], v[140:143], v[218:221], 0
	v_mfma_f32_16x16x32_bf16 v[12:15], v[132:135], v[242:245], 0
	v_mfma_f32_16x16x32_bf16 v[8:11], v[140:143], v[242:245], 0
	v_mfma_f32_16x16x32_bf16 v[60:63], v[136:139], v[194:197], v[60:63]
	v_mfma_f32_16x16x32_bf16 v[56:59], v[158:161], v[194:197], v[56:59]
	v_mfma_f32_16x16x32_bf16 v[44:47], v[136:139], v[204:207], v[44:47]
	v_mfma_f32_16x16x32_bf16 v[40:43], v[158:161], v[204:207], v[40:43]
	v_mfma_f32_16x16x32_bf16 v[28:31], v[136:139], v[238:241], v[28:31]
	v_mfma_f32_16x16x32_bf16 v[24:27], v[158:161], v[238:241], v[24:27]
	v_mfma_f32_16x16x32_bf16 v[12:15], v[136:139], v[246:249], v[12:15]
	v_mfma_f32_16x16x32_bf16 v[8:11], v[158:161], v[246:249], v[8:11]
	s_setprio 0
	s_setprio 1
	v_mfma_f32_16x16x32_bf16 v[52:55], v[162:165], v[190:193], 0
	v_mfma_f32_16x16x32_bf16 v[48:51], v[182:185], v[190:193], 0
	v_mfma_f32_16x16x32_bf16 v[36:39], v[162:165], v[198:201], 0
	v_mfma_f32_16x16x32_bf16 v[32:35], v[182:185], v[198:201], 0
	v_mfma_f32_16x16x32_bf16 v[20:23], v[162:165], v[218:221], 0
	v_mfma_f32_16x16x32_bf16 v[16:19], v[182:185], v[218:221], 0
	v_mfma_f32_16x16x32_bf16 v[4:7], v[162:165], v[242:245], 0
	v_mfma_f32_16x16x32_bf16 v[0:3], v[182:185], v[242:245], 0
	v_mfma_f32_16x16x32_bf16 v[52:55], v[166:169], v[194:197], v[52:55]
	v_mfma_f32_16x16x32_bf16 v[48:51], v[186:189], v[194:197], v[48:51]
	v_mfma_f32_16x16x32_bf16 v[36:39], v[166:169], v[204:207], v[36:39]
	v_mfma_f32_16x16x32_bf16 v[32:35], v[186:189], v[204:207], v[32:35]
	v_mfma_f32_16x16x32_bf16 v[20:23], v[166:169], v[238:241], v[20:23]
	v_mfma_f32_16x16x32_bf16 v[16:19], v[186:189], v[238:241], v[16:19]
	v_mfma_f32_16x16x32_bf16 v[4:7], v[166:169], v[246:249], v[4:7]
	s_barrier
	v_mfma_f32_16x16x32_bf16 v[0:3], v[186:189], v[246:249], v[0:3]
	s_setprio 0
	s_add_i32 s85, 0, 0x18000
	s_add_i32 s86, 0, 0x1c000
	v_add_u32_e32 v158, s85, v174
	v_add_u32_e32 v186, s86, v174
	ds_read_b128 v[132:135], v158
	ds_read_b128 v[136:139], v158 offset:1024
	ds_read_b128 v[140:143], v158 offset:2048
	ds_read_b128 v[158:161], v158 offset:3072
	ds_read_b128 v[162:165], v186
	ds_read_b128 v[166:169], v186 offset:1024
	ds_read_b128 v[182:185], v186 offset:2048
	ds_read_b128 v[186:189], v186 offset:3072
	s_add_u32 s48, s48, 0x40000
	s_addc_u32 s49, s49, 0
	s_mov_b32 m0, s58
	v_lshl_add_u64 v[250:251], s[48:49], 0, v[144:145]
	ds_read_b128 v[190:193], v180 offset:32768
	ds_read_b128 v[194:197], v180 offset:33792
	ds_read_b128 v[198:201], v180 offset:34816
	ds_read_b128 v[204:207], v180 offset:35840
	ds_read_b128 v[218:221], v180 offset:36864
	ds_read_b128 v[238:241], v180 offset:37888
	ds_read_b128 v[242:245], v180 offset:38912
	ds_read_b128 v[246:249], v180 offset:39936
	global_load_lds_dwordx4 v[250:251], off
	v_lshl_add_u64 v[250:251], s[48:49], 0, v[148:149]
	s_mov_b32 m0, s59
	s_nop 0
	global_load_lds_dwordx4 v[250:251], off
	s_waitcnt vmcnt(8)
	s_waitcnt lgkmcnt(0)
	s_barrier
	s_setprio 1
	s_waitcnt lgkmcnt(0)
	v_mfma_f32_16x16x32_bf16 v[124:127], v[132:135], v[190:193], v[124:127]
	v_mfma_f32_16x16x32_bf16 v[120:123], v[140:143], v[190:193], v[120:123]
	v_mfma_f32_16x16x32_bf16 v[108:111], v[132:135], v[198:201], v[108:111]
	v_mfma_f32_16x16x32_bf16 v[104:107], v[140:143], v[198:201], v[104:107]
	v_mfma_f32_16x16x32_bf16 v[92:95], v[132:135], v[218:221], v[92:95]
	v_mfma_f32_16x16x32_bf16 v[88:91], v[140:143], v[218:221], v[88:91]
	v_mfma_f32_16x16x32_bf16 v[76:79], v[132:135], v[242:245], v[76:79]
	v_mfma_f32_16x16x32_bf16 v[72:75], v[140:143], v[242:245], v[72:75]
	v_mfma_f32_16x16x32_bf16 v[124:127], v[136:139], v[194:197], v[124:127]
	v_mfma_f32_16x16x32_bf16 v[120:123], v[158:161], v[194:197], v[120:123]
	v_mfma_f32_16x16x32_bf16 v[108:111], v[136:139], v[204:207], v[108:111]
	v_mfma_f32_16x16x32_bf16 v[104:107], v[158:161], v[204:207], v[104:107]
	v_mfma_f32_16x16x32_bf16 v[92:95], v[136:139], v[238:241], v[92:95]
	v_mfma_f32_16x16x32_bf16 v[88:91], v[158:161], v[238:241], v[88:91]
	v_mfma_f32_16x16x32_bf16 v[76:79], v[136:139], v[246:249], v[76:79]
	v_mfma_f32_16x16x32_bf16 v[72:75], v[158:161], v[246:249], v[72:75]
	s_setprio 0
	s_setprio 1
	v_mfma_f32_16x16x32_bf16 v[116:119], v[162:165], v[190:193], v[116:119]
	v_mfma_f32_16x16x32_bf16 v[112:115], v[182:185], v[190:193], v[112:115]
	v_mfma_f32_16x16x32_bf16 v[100:103], v[162:165], v[198:201], v[100:103]
	v_mfma_f32_16x16x32_bf16 v[96:99], v[182:185], v[198:201], v[96:99]
	v_mfma_f32_16x16x32_bf16 v[84:87], v[162:165], v[218:221], v[84:87]
	v_mfma_f32_16x16x32_bf16 v[80:83], v[182:185], v[218:221], v[80:83]
	v_mfma_f32_16x16x32_bf16 v[68:71], v[162:165], v[242:245], v[68:71]
	v_mfma_f32_16x16x32_bf16 v[64:67], v[182:185], v[242:245], v[64:67]
	v_mfma_f32_16x16x32_bf16 v[116:119], v[166:169], v[194:197], v[116:119]
	v_mfma_f32_16x16x32_bf16 v[112:115], v[186:189], v[194:197], v[112:115]
	v_mfma_f32_16x16x32_bf16 v[100:103], v[166:169], v[204:207], v[100:103]
	v_mfma_f32_16x16x32_bf16 v[96:99], v[186:189], v[204:207], v[96:99]
	v_mfma_f32_16x16x32_bf16 v[84:87], v[166:169], v[238:241], v[84:87]
	v_mfma_f32_16x16x32_bf16 v[80:83], v[186:189], v[238:241], v[80:83]
	v_mfma_f32_16x16x32_bf16 v[68:71], v[166:169], v[246:249], v[68:71]
	s_barrier
; #define PG8_STAGE(bufoff, gbase, voff) do { _Pragma("unroll") for (int _i = 0; _i < 2; ++_i) \
;         __builtin_amdgcn_global_load_lds((const unsigned*)((const char*)(gbase) + (voff)[_i]), (PG8_LAS unsigned*)(lds + (bufoff) + ldsw + _i * 8192), 16, 0, 0); } while (0)
; #define PG8_LDA(dst, b, h) do { _Pragma("unroll") for (int m = 0; m < 4; ++m) _Pragma("unroll") for (int k = 0; k < 2; ++k) dst[m][k] = *(const PG8_LAS bf16x8*)(lds + PG8_SA(b, h) + aoff + m * 2048 + k * 1024); } while (0)
; #define PG8_MMA(ai, bj, At, Bt) do { __builtin_amdgcn_s_setprio(1); _Pragma("unroll") for (int m = 0; m < 4; ++m) _Pragma("unroll") for (int n = 0; n < 2; ++n) _Pragma("unroll") for (int k = 0; k < 2; ++k) \
;         acc[ai][bj][m][n] = __builtin_amdgcn_mfma_f32_16x16x32_bf16(Bt[n][k], At[m][k], acc[ai][bj][m][n], 0, 0, 0); __builtin_amdgcn_s_setprio(0); } while (0)
; #define PG8_WAIT_V(n) asm volatile("s_waitcnt vmcnt(" #n ")" ::: "memory")
; #define PG8_WAIT_L(n) asm volatile("s_waitcnt lgkmcnt(" #n ")" ::: "memory")
; #define PG8_BAR __builtin_amdgcn_s_barrier()
; #define PG8_SCHED __builtin_amdgcn_sched_barrier(0)
;     ...
;             PG8_LDA(At, 1, 1); PG8_STAGE(PG8_SB(1, 0), b3, voffB); PG8_STAGE(PG8_SB(1, 1), b3 + hstepB, voffB); PG8_STAGE(PG8_SA(1, 0), a3, voffA);
;             PG8_WAIT_V(8); PG8_WAIT_L(0); PG8_BAR; PG8_MMA(1, 0, At, B0); PG8_MMA(1, 1, At, B1); PG8_BAR; PG8_SCHED;
;         }
	v_mfma_f32_16x16x32_bf16 v[64:67], v[186:189], v[246:249], v[64:67]
	s_setprio 0
	s_add_i32 s48, s85, s52
	v_lshl_add_u64 v[222:223], v[222:223], 0, s[90:91]
	s_mov_b32 m0, s48
	ds_read_b128 v[190:193], v180 offset:49152
	ds_read_b128 v[194:197], v180 offset:50176
	ds_read_b128 v[198:201], v180 offset:51200
	ds_read_b128 v[204:207], v180 offset:52224
	ds_read_b128 v[218:221], v180 offset:53248
	ds_read_b128 v[238:241], v180 offset:54272
	ds_read_b128 v[242:245], v180 offset:55296
	ds_read_b128 v[246:249], v180 offset:56320
	global_load_lds_dwordx4 v[222:223], off
	s_add_i32 m0, s48, 0x2000
	s_add_u32 s46, s46, 0x40080
	v_lshl_add_u64 v[222:223], v[224:225], 0, s[90:91]
	s_addc_u32 s47, s47, 0
	s_add_i32 s48, s86, s52
	global_load_lds_dwordx4 v[222:223], off
	v_lshl_add_u64 v[222:223], s[46:47], 0, v[146:147]
	s_mov_b32 m0, s48
	s_nop 0
	global_load_lds_dwordx4 v[222:223], off
	v_lshl_add_u64 v[222:223], s[46:47], 0, v[150:151]
	s_add_i32 m0, s48, 0x2000
	s_nop 0
	global_load_lds_dwordx4 v[222:223], off
	v_lshl_add_u64 v[222:223], s[28:29], 0, v[144:145]
	s_mov_b32 m0, s60
	s_nop 0
	global_load_lds_dwordx4 v[222:223], off
	v_lshl_add_u64 v[222:223], s[28:29], 0, v[148:149]
	s_mov_b32 m0, s61
	s_nop 0
	global_load_lds_dwordx4 v[222:223], off
	s_waitcnt vmcnt(8)
	s_waitcnt lgkmcnt(0)
	s_barrier
	s_setprio 1
	s_waitcnt lgkmcnt(0)
	v_mfma_f32_16x16x32_bf16 v[60:63], v[132:135], v[190:193], v[60:63]
	v_mfma_f32_16x16x32_bf16 v[56:59], v[140:143], v[190:193], v[56:59]
	v_mfma_f32_16x16x32_bf16 v[44:47], v[132:135], v[198:201], v[44:47]
	v_mfma_f32_16x16x32_bf16 v[40:43], v[140:143], v[198:201], v[40:43]
	v_mfma_f32_16x16x32_bf16 v[28:31], v[132:135], v[218:221], v[28:31]
	v_mfma_f32_16x16x32_bf16 v[24:27], v[140:143], v[218:221], v[24:27]
	v_mfma_f32_16x16x32_bf16 v[12:15], v[132:135], v[242:245], v[12:15]
	v_mfma_f32_16x16x32_bf16 v[8:11], v[140:143], v[242:245], v[8:11]
	v_mfma_f32_16x16x32_bf16 v[60:63], v[136:139], v[194:197], v[60:63]
	v_mfma_f32_16x16x32_bf16 v[56:59], v[158:161], v[194:197], v[56:59]
	v_mfma_f32_16x16x32_bf16 v[44:47], v[136:139], v[204:207], v[44:47]
	v_mfma_f32_16x16x32_bf16 v[40:43], v[158:161], v[204:207], v[40:43]
	v_mfma_f32_16x16x32_bf16 v[28:31], v[136:139], v[238:241], v[28:31]
	v_mfma_f32_16x16x32_bf16 v[24:27], v[158:161], v[238:241], v[24:27]
	v_mfma_f32_16x16x32_bf16 v[12:15], v[136:139], v[246:249], v[12:15]
	v_mfma_f32_16x16x32_bf16 v[8:11], v[158:161], v[246:249], v[8:11]
	s_setprio 0
	s_setprio 1
	v_mfma_f32_16x16x32_bf16 v[52:55], v[162:165], v[190:193], v[52:55]
	v_mfma_f32_16x16x32_bf16 v[48:51], v[182:185], v[190:193], v[48:51]
	v_mfma_f32_16x16x32_bf16 v[36:39], v[162:165], v[198:201], v[36:39]
	v_mfma_f32_16x16x32_bf16 v[32:35], v[182:185], v[198:201], v[32:35]
	v_mfma_f32_16x16x32_bf16 v[20:23], v[162:165], v[218:221], v[20:23]
	v_mfma_f32_16x16x32_bf16 v[16:19], v[182:185], v[218:221], v[16:19]
	v_mfma_f32_16x16x32_bf16 v[4:7], v[162:165], v[242:245], v[4:7]
	v_mfma_f32_16x16x32_bf16 v[0:3], v[182:185], v[242:245], v[0:3]
	v_mfma_f32_16x16x32_bf16 v[52:55], v[166:169], v[194:197], v[52:55]
	v_mfma_f32_16x16x32_bf16 v[48:51], v[186:189], v[194:197], v[48:51]
	v_mfma_f32_16x16x32_bf16 v[36:39], v[166:169], v[204:207], v[36:39]
	v_mfma_f32_16x16x32_bf16 v[32:35], v[186:189], v[204:207], v[32:35]
	v_mfma_f32_16x16x32_bf16 v[20:23], v[166:169], v[238:241], v[20:23]
	v_mfma_f32_16x16x32_bf16 v[16:19], v[186:189], v[238:241], v[16:19]
	v_mfma_f32_16x16x32_bf16 v[4:7], v[166:169], v[246:249], v[4:7]
	s_barrier
	v_mfma_f32_16x16x32_bf16 v[0:3], v[186:189], v[246:249], v[0:3]
	s_setprio 0
	s_add_i32 s84, s84, 2
	s_add_u32 s2, s2, 0x100
	s_addc_u32 s3, s3, 0
	s_cmp_gt_u32 s84, 13
	s_cbranch_scc0 .LBB0_380
	s_branch .Lpeel_exit_380
	.p2alignl 6, 3212836864

;     __device__ __forceinline__ const char* tile(const Unit& u, int t) const { return A + (size_t)u.pm * 2 * hstep() + (size_t)t * (BK * 2); }
;     __device__ __forceinline__ const char* tile(const Unit& u, int t) const { return U + (long)(t >> 2) * xoff + (size_t)u.pn * (1024 * 512) + (size_t)u.pm * 2 * hstep() + (size_t)(t & 3) * (BK * 2); }
; #define PG8_STAGE(bufoff, gbase, voff) do { _Pragma("unroll") for (int _i = 0; _i < 2; ++_i) \
;         __builtin_amdgcn_global_load_lds((const unsigned*)((const char*)(gbase) + (voff)[_i]), (PG8_LAS unsigned*)(lds + (bufoff) + ldsw + _i * 8192), 16, 0, 0); } while (0)
; #define PG8_LDA(dst, b, h) do { _Pragma("unroll") for (int m = 0; m < 4; ++m) _Pragma("unroll") for (int k = 0; k < 2; ++k) dst[m][k] = *(const PG8_LAS bf16x8*)(lds + PG8_SA(b, h) + aoff + m * 2048 + k * 1024); } while (0)
; #define PG8_LDB(dst, b, h) do { _Pragma("unroll") for (int n = 0; n < 2; ++n) _Pragma("unroll") for (int k = 0; k < 2; ++k) dst[n][k] = *(const PG8_LAS bf16x8*)(lds + PG8_SB(b, h) + boff + n * 2048 + k * 1024); } while (0)
; #define PG8_MMA(ai, bj, At, Bt) do { __builtin_amdgcn_s_setprio(1); _Pragma("unroll") for (int m = 0; m < 4; ++m) _Pragma("unroll") for (int n = 0; n < 2; ++n) _Pragma("unroll") for (int k = 0; k < 2; ++k) \
;         acc[ai][bj][m][n] = __builtin_amdgcn_mfma_f32_16x16x32_bf16(Bt[n][k], At[m][k], acc[ai][bj][m][n], 0, 0, 0); __builtin_amdgcn_s_setprio(0); } while (0)
; #define PG8_BAR __builtin_amdgcn_s_barrier()
;     ...
;         for (int t = 0; t < nt; t += 2) {
;             const bool last = (t == nt - 2);
;             const char* a1 = AS.tile(cur, t + 1);
;             const char* a2 = last ? AS.tile(nu, 0) : AS.tile(cur, t + 2); const char* b2 = last ? nB : cB + (size_t)(t + 2) * kstep;
;             const char* a3 = last ? AS.tile(nu, 1) : AS.tile(cur, t + 3); const char* b3 = b2 + kstep;
;             PG8_LDB(B0, 0, 0); PG8_LDB(B1, 0, 1); PG8_SCHED; PG8_LDA(At, 0, 0); PG8_STAGE(PG8_SA(1, 1), a1 + hstepA, voffA);
;             PG8_WAIT_V(8); PG8_WAIT_L(0); PG8_BAR; PG8_MMA(0, 0, At, B0); PG8_MMA(0, 1, At, B1); PG8_BAR; PG8_SCHED;
;             PG8_LDA(At, 0, 1); PG8_STAGE(PG8_SB(0, 0), b2, voffB); PG8_STAGE(PG8_SB(0, 1), b2 + hstepB, voffB); PG8_STAGE(PG8_SA(0, 0), a2, voffA);
;             PG8_WAIT_V(8); PG8_WAIT_L(0); PG8_BAR; PG8_MMA(1, 0, At, B0); PG8_MMA(1, 1, At, B1); PG8_BAR; PG8_SCHED;
.Lpeel_451:
	s_add_u32 s20, s61, s18
	s_addc_u32 s21, s64, s19
	s_add_u32 s26, s20, 0x3600100
	s_addc_u32 s27, s21, 0
	s_add_u32 s24, s65, s18
	s_addc_u32 s25, s66, s19
	s_add_u32 s20, s20, 0x3600180
	s_addc_u32 s21, s21, 0
	s_add_i32 s68, 0, 0x10000
	s_add_i32 s70, 0, 0x14000
	v_add_u32_e32 v144, s68, v203
	v_add_u32_e32 v174, s70, v203
	ds_read_b128 v[132:135], v144
	ds_read_b128 v[136:139], v144 offset:1024
	ds_read_b128 v[140:143], v144 offset:2048
	ds_read_b128 v[144:147], v144 offset:3072
	ds_read_b128 v[148:151], v174
	ds_read_b128 v[152:155], v174 offset:1024
	ds_read_b128 v[170:173], v174 offset:2048
	ds_read_b128 v[174:177], v174 offset:3072
	s_cmpk_eq_i32 s18, 0x700
	s_cselect_b32 s21, s60, s21
	s_cselect_b32 s20, s59, s20
	s_cselect_b32 s25, s57, s25
	s_cselect_b32 s24, s56, s24
	s_cselect_b32 s27, s58, s27
	s_cselect_b32 s26, s3, s26
	v_lshl_add_u64 v[238:239], v[112:113], 0, s[18:19]
	s_add_i32 m0, s35, 0xc000
	ds_read_b128 v[178:181], v211
	ds_read_b128 v[182:185], v211 offset:1024
	ds_read_b128 v[186:189], v211 offset:2048
	ds_read_b128 v[190:193], v211 offset:3072
	ds_read_b128 v[194:197], v211 offset:4096
	ds_read_b128 v[198:201], v211 offset:5120
	ds_read_b128 v[218:221], v211 offset:6144
	ds_read_b128 v[222:225], v211 offset:7168
	global_load_lds_dwordx4 v[238:239], off
	v_lshl_add_u64 v[238:239], v[114:115], 0, s[18:19]
	s_add_i32 m0, s35, 0xe000
	s_nop 0
	global_load_lds_dwordx4 v[238:239], off
	s_waitcnt vmcnt(24)
	s_waitcnt lgkmcnt(0)
	s_barrier
	s_setprio 1
	s_waitcnt lgkmcnt(0)
	v_mfma_f32_16x16x32_bf16 v[120:123], v[132:135], v[178:181], 0
	v_mfma_f32_16x16x32_bf16 v[116:119], v[140:143], v[178:181], 0
	v_mfma_f32_16x16x32_bf16 v[108:111], v[132:135], v[186:189], 0
	v_mfma_f32_16x16x32_bf16 v[104:107], v[140:143], v[186:189], 0
	v_mfma_f32_16x16x32_bf16 v[92:95], v[132:135], v[194:197], 0
	v_mfma_f32_16x16x32_bf16 v[88:91], v[140:143], v[194:197], 0
	v_mfma_f32_16x16x32_bf16 v[76:79], v[132:135], v[218:221], 0
	v_mfma_f32_16x16x32_bf16 v[72:75], v[140:143], v[218:221], 0
	v_mfma_f32_16x16x32_bf16 v[120:123], v[136:139], v[182:185], v[120:123]
	v_mfma_f32_16x16x32_bf16 v[116:119], v[144:147], v[182:185], v[116:119]
	v_mfma_f32_16x16x32_bf16 v[108:111], v[136:139], v[190:193], v[108:111]
	v_mfma_f32_16x16x32_bf16 v[104:107], v[144:147], v[190:193], v[104:107]
	v_mfma_f32_16x16x32_bf16 v[92:95], v[136:139], v[198:201], v[92:95]
	v_mfma_f32_16x16x32_bf16 v[88:91], v[144:147], v[198:201], v[88:91]
	v_mfma_f32_16x16x32_bf16 v[76:79], v[136:139], v[222:225], v[76:79]
	v_mfma_f32_16x16x32_bf16 v[72:75], v[144:147], v[222:225], v[72:75]
	s_setprio 0
	s_setprio 1
	v_mfma_f32_16x16x32_bf16 v[128:131], v[148:151], v[178:181], 0
	v_mfma_f32_16x16x32_bf16 v[124:127], v[170:173], v[178:181], 0
	v_mfma_f32_16x16x32_bf16 v[100:103], v[148:151], v[186:189], 0
	v_mfma_f32_16x16x32_bf16 v[96:99], v[170:173], v[186:189], 0
	v_mfma_f32_16x16x32_bf16 v[84:87], v[148:151], v[194:197], 0
	v_mfma_f32_16x16x32_bf16 v[80:83], v[170:173], v[194:197], 0
	v_mfma_f32_16x16x32_bf16 v[68:71], v[148:151], v[218:221], 0
	v_mfma_f32_16x16x32_bf16 v[64:67], v[170:173], v[218:221], 0
	v_mfma_f32_16x16x32_bf16 v[128:131], v[152:155], v[182:185], v[128:131]
	v_mfma_f32_16x16x32_bf16 v[124:127], v[174:177], v[182:185], v[124:127]
	v_mfma_f32_16x16x32_bf16 v[100:103], v[152:155], v[190:193], v[100:103]
	v_mfma_f32_16x16x32_bf16 v[96:99], v[174:177], v[190:193], v[96:99]
	v_mfma_f32_16x16x32_bf16 v[84:87], v[152:155], v[198:201], v[84:87]
	v_mfma_f32_16x16x32_bf16 v[80:83], v[174:177], v[198:201], v[80:83]
	v_mfma_f32_16x16x32_bf16 v[68:71], v[152:155], v[222:225], v[68:71]
	s_barrier
	v_mfma_f32_16x16x32_bf16 v[64:67], v[174:177], v[222:225], v[64:67]
	s_setprio 0
	s_add_i32 s68, s68, s31
	v_lshl_add_u64 v[238:239], s[24:25], 0, v[208:209]
	s_mov_b32 m0, s68
	ds_read_b128 v[178:181], v211 offset:16384
	ds_read_b128 v[182:185], v211 offset:17408
	ds_read_b128 v[186:189], v211 offset:18432
	ds_read_b128 v[190:193], v211 offset:19456
	ds_read_b128 v[194:197], v211 offset:20480
	ds_read_b128 v[198:201], v211 offset:21504
	ds_read_b128 v[218:221], v211 offset:22528
	ds_read_b128 v[222:225], v211 offset:23552
	global_load_lds_dwordx4 v[238:239], off
	s_add_i32 m0, s68, 0x2000
	s_add_u32 s68, s24, 0x40000
	v_lshl_add_u64 v[240:241], s[24:25], 0, v[156:157]
	s_addc_u32 s69, s25, 0
	s_add_i32 s70, s70, s31
	global_load_lds_dwordx4 v[240:241], off
	v_lshl_add_u64 v[242:243], s[68:69], 0, v[208:209]
	s_mov_b32 m0, s70
	s_nop 0
	global_load_lds_dwordx4 v[242:243], off
	v_lshl_add_u64 v[242:243], s[68:69], 0, v[156:157]
	s_add_i32 m0, s70, 0x2000
	s_nop 0
	global_load_lds_dwordx4 v[242:243], off
	v_lshl_add_u64 v[242:243], s[26:27], 0, v[160:161]
	s_mov_b32 m0, s35
	s_nop 0
	global_load_lds_dwordx4 v[242:243], off
	v_lshl_add_u64 v[242:243], s[26:27], 0, v[158:159]
	s_mov_b32 m0, s44
	s_nop 0
	global_load_lds_dwordx4 v[242:243], off
	s_waitcnt vmcnt(8)
	s_waitcnt lgkmcnt(0)
	s_barrier
; #define PG8_STAGE(bufoff, gbase, voff) do { _Pragma("unroll") for (int _i = 0; _i < 2; ++_i) \
;         __builtin_amdgcn_global_load_lds((const unsigned*)((const char*)(gbase) + (voff)[_i]), (PG8_LAS unsigned*)(lds + (bufoff) + ldsw + _i * 8192), 16, 0, 0); } while (0)
; #define PG8_LDA(dst, b, h) do { _Pragma("unroll") for (int m = 0; m < 4; ++m) _Pragma("unroll") for (int k = 0; k < 2; ++k) dst[m][k] = *(const PG8_LAS bf16x8*)(lds + PG8_SA(b, h) + aoff + m * 2048 + k * 1024); } while (0)
; #define PG8_LDB(dst, b, h) do { _Pragma("unroll") for (int n = 0; n < 2; ++n) _Pragma("unroll") for (int k = 0; k < 2; ++k) dst[n][k] = *(const PG8_LAS bf16x8*)(lds + PG8_SB(b, h) + boff + n * 2048 + k * 1024); } while (0)
; #define PG8_MMA(ai, bj, At, Bt) do { __builtin_amdgcn_s_setprio(1); _Pragma("unroll") for (int m = 0; m < 4; ++m) _Pragma("unroll") for (int n = 0; n < 2; ++n) _Pragma("unroll") for (int k = 0; k < 2; ++k) \
;         acc[ai][bj][m][n] = __builtin_amdgcn_mfma_f32_16x16x32_bf16(Bt[n][k], At[m][k], acc[ai][bj][m][n], 0, 0, 0); __builtin_amdgcn_s_setprio(0); } while (0)
; #define PG8_WAIT_V(n) asm volatile("s_waitcnt vmcnt(" #n ")" ::: "memory")
; #define PG8_WAIT_L(n) asm volatile("s_waitcnt lgkmcnt(" #n ")" ::: "memory")
; #define PG8_BAR __builtin_amdgcn_s_barrier()
; #define PG8_SCHED __builtin_amdgcn_sched_barrier(0)
;     ...
;             PG8_WAIT_V(8); PG8_WAIT_L(0); PG8_BAR; PG8_MMA(1, 0, At, B0); PG8_MMA(1, 1, At, B1); PG8_BAR; PG8_SCHED;
;             PG8_LDB(B0, 1, 0); PG8_LDB(B1, 1, 1); PG8_SCHED; PG8_LDA(At, 1, 0); PG8_STAGE(PG8_SA(0, 1), a2 + hstepA, voffA);
;             PG8_WAIT_V(8); PG8_WAIT_L(0); PG8_BAR; PG8_MMA(0, 0, At, B0); PG8_MMA(0, 1, At, B1); PG8_BAR; PG8_SCHED;
;             PG8_LDA(At, 1, 1); PG8_STAGE(PG8_SB(1, 0), b3, voffB); PG8_STAGE(PG8_SB(1, 1), b3 + hstepB, voffB); PG8_STAGE(PG8_SA(1, 0), a3, voffA);
	s_setprio 1
	s_waitcnt lgkmcnt(0)
	v_mfma_f32_16x16x32_bf16 v[60:63], v[132:135], v[178:181], 0
	v_mfma_f32_16x16x32_bf16 v[56:59], v[140:143], v[178:181], 0
	v_mfma_f32_16x16x32_bf16 v[44:47], v[132:135], v[186:189], 0
	v_mfma_f32_16x16x32_bf16 v[40:43], v[140:143], v[186:189], 0
	v_mfma_f32_16x16x32_bf16 v[28:31], v[132:135], v[194:197], 0
	v_mfma_f32_16x16x32_bf16 v[24:27], v[140:143], v[194:197], 0
	v_mfma_f32_16x16x32_bf16 v[12:15], v[132:135], v[218:221], 0
	v_mfma_f32_16x16x32_bf16 v[8:11], v[140:143], v[218:221], 0
	v_mfma_f32_16x16x32_bf16 v[60:63], v[136:139], v[182:185], v[60:63]
	v_mfma_f32_16x16x32_bf16 v[56:59], v[144:147], v[182:185], v[56:59]
	v_mfma_f32_16x16x32_bf16 v[44:47], v[136:139], v[190:193], v[44:47]
	v_mfma_f32_16x16x32_bf16 v[40:43], v[144:147], v[190:193], v[40:43]
	v_mfma_f32_16x16x32_bf16 v[28:31], v[136:139], v[198:201], v[28:31]
	v_mfma_f32_16x16x32_bf16 v[24:27], v[144:147], v[198:201], v[24:27]
	v_mfma_f32_16x16x32_bf16 v[12:15], v[136:139], v[222:225], v[12:15]
	v_mfma_f32_16x16x32_bf16 v[8:11], v[144:147], v[222:225], v[8:11]
	s_setprio 0
	s_setprio 1
	v_mfma_f32_16x16x32_bf16 v[52:55], v[148:151], v[178:181], 0
	v_mfma_f32_16x16x32_bf16 v[48:51], v[170:173], v[178:181], 0
	v_mfma_f32_16x16x32_bf16 v[36:39], v[148:151], v[186:189], 0
	v_mfma_f32_16x16x32_bf16 v[32:35], v[170:173], v[186:189], 0
	v_mfma_f32_16x16x32_bf16 v[20:23], v[148:151], v[194:197], 0
	v_mfma_f32_16x16x32_bf16 v[16:19], v[170:173], v[194:197], 0
	v_mfma_f32_16x16x32_bf16 v[4:7], v[148:151], v[218:221], 0
	v_mfma_f32_16x16x32_bf16 v[0:3], v[170:173], v[218:221], 0
	v_mfma_f32_16x16x32_bf16 v[52:55], v[152:155], v[182:185], v[52:55]
	v_mfma_f32_16x16x32_bf16 v[48:51], v[174:177], v[182:185], v[48:51]
	v_mfma_f32_16x16x32_bf16 v[36:39], v[152:155], v[190:193], v[36:39]
	v_mfma_f32_16x16x32_bf16 v[32:35], v[174:177], v[190:193], v[32:35]
	v_mfma_f32_16x16x32_bf16 v[20:23], v[152:155], v[198:201], v[20:23]
	v_mfma_f32_16x16x32_bf16 v[16:19], v[174:177], v[198:201], v[16:19]
	v_mfma_f32_16x16x32_bf16 v[4:7], v[152:155], v[222:225], v[4:7]
	s_barrier
	v_mfma_f32_16x16x32_bf16 v[0:3], v[174:177], v[222:225], v[0:3]
	s_setprio 0
	s_add_i32 s68, 0, 0x18000
	s_add_i32 s69, 0, 0x1c000
	v_add_u32_e32 v144, s68, v203
	v_add_u32_e32 v174, s69, v203
	ds_read_b128 v[132:135], v144
	ds_read_b128 v[136:139], v144 offset:1024
	ds_read_b128 v[140:143], v144 offset:2048
	ds_read_b128 v[144:147], v144 offset:3072
	ds_read_b128 v[148:151], v174
	ds_read_b128 v[152:155], v174 offset:1024
	ds_read_b128 v[170:173], v174 offset:2048
	ds_read_b128 v[174:177], v174 offset:3072
	s_add_u32 s26, s26, 0x40000
	s_addc_u32 s27, s27, 0
	s_mov_b32 m0, s45
	v_lshl_add_u64 v[242:243], s[26:27], 0, v[160:161]
	ds_read_b128 v[178:181], v211 offset:32768
	ds_read_b128 v[182:185], v211 offset:33792
	ds_read_b128 v[186:189], v211 offset:34816
	ds_read_b128 v[190:193], v211 offset:35840
	ds_read_b128 v[194:197], v211 offset:36864
	ds_read_b128 v[198:201], v211 offset:37888
	ds_read_b128 v[218:221], v211 offset:38912
	ds_read_b128 v[222:225], v211 offset:39936
	global_load_lds_dwordx4 v[242:243], off
	v_lshl_add_u64 v[242:243], s[26:27], 0, v[158:159]
	s_mov_b32 m0, s46
	s_nop 0
	global_load_lds_dwordx4 v[242:243], off
	s_waitcnt vmcnt(8)
	s_waitcnt lgkmcnt(0)
	s_barrier
	s_setprio 1
	s_waitcnt lgkmcnt(0)
	v_mfma_f32_16x16x32_bf16 v[120:123], v[132:135], v[178:181], v[120:123]
	v_mfma_f32_16x16x32_bf16 v[116:119], v[140:143], v[178:181], v[116:119]
	v_mfma_f32_16x16x32_bf16 v[108:111], v[132:135], v[186:189], v[108:111]
	v_mfma_f32_16x16x32_bf16 v[104:107], v[140:143], v[186:189], v[104:107]
	v_mfma_f32_16x16x32_bf16 v[92:95], v[132:135], v[194:197], v[92:95]
	v_mfma_f32_16x16x32_bf16 v[88:91], v[140:143], v[194:197], v[88:91]
	v_mfma_f32_16x16x32_bf16 v[76:79], v[132:135], v[218:221], v[76:79]
	v_mfma_f32_16x16x32_bf16 v[72:75], v[140:143], v[218:221], v[72:75]
	v_mfma_f32_16x16x32_bf16 v[120:123], v[136:139], v[182:185], v[120:123]
	v_mfma_f32_16x16x32_bf16 v[116:119], v[144:147], v[182:185], v[116:119]
	v_mfma_f32_16x16x32_bf16 v[108:111], v[136:139], v[190:193], v[108:111]
	v_mfma_f32_16x16x32_bf16 v[104:107], v[144:147], v[190:193], v[104:107]
	v_mfma_f32_16x16x32_bf16 v[92:95], v[136:139], v[198:201], v[92:95]
	v_mfma_f32_16x16x32_bf16 v[88:91], v[144:147], v[198:201], v[88:91]
	v_mfma_f32_16x16x32_bf16 v[76:79], v[136:139], v[222:225], v[76:79]
	v_mfma_f32_16x16x32_bf16 v[72:75], v[144:147], v[222:225], v[72:75]
	s_setprio 0
	s_setprio 1
	v_mfma_f32_16x16x32_bf16 v[128:131], v[148:151], v[178:181], v[128:131]
	v_mfma_f32_16x16x32_bf16 v[124:127], v[170:173], v[178:181], v[124:127]
	v_mfma_f32_16x16x32_bf16 v[100:103], v[148:151], v[186:189], v[100:103]
	v_mfma_f32_16x16x32_bf16 v[96:99], v[170:173], v[186:189], v[96:99]
	v_mfma_f32_16x16x32_bf16 v[84:87], v[148:151], v[194:197], v[84:87]
	v_mfma_f32_16x16x32_bf16 v[80:83], v[170:173], v[194:197], v[80:83]
	v_mfma_f32_16x16x32_bf16 v[68:71], v[148:151], v[218:221], v[68:71]
	v_mfma_f32_16x16x32_bf16 v[64:67], v[170:173], v[218:221], v[64:67]
	v_mfma_f32_16x16x32_bf16 v[128:131], v[152:155], v[182:185], v[128:131]
	v_mfma_f32_16x16x32_bf16 v[124:127], v[174:177], v[182:185], v[124:127]
	v_mfma_f32_16x16x32_bf16 v[100:103], v[152:155], v[190:193], v[100:103]
	v_mfma_f32_16x16x32_bf16 v[96:99], v[174:177], v[190:193], v[96:99]
	v_mfma_f32_16x16x32_bf16 v[84:87], v[152:155], v[198:201], v[84:87]
	v_mfma_f32_16x16x32_bf16 v[80:83], v[174:177], v[198:201], v[80:83]
	v_mfma_f32_16x16x32_bf16 v[68:71], v[152:155], v[222:225], v[68:71]
	s_barrier
; #define PG8_STAGE(bufoff, gbase, voff) do { _Pragma("unroll") for (int _i = 0; _i < 2; ++_i) \
;         __builtin_amdgcn_global_load_lds((const unsigned*)((const char*)(gbase) + (voff)[_i]), (PG8_LAS unsigned*)(lds + (bufoff) + ldsw + _i * 8192), 16, 0, 0); } while (0)
; #define PG8_LDA(dst, b, h) do { _Pragma("unroll") for (int m = 0; m < 4; ++m) _Pragma("unroll") for (int k = 0; k < 2; ++k) dst[m][k] = *(const PG8_LAS bf16x8*)(lds + PG8_SA(b, h) + aoff + m * 2048 + k * 1024); } while (0)
; #define PG8_MMA(ai, bj, At, Bt) do { __builtin_amdgcn_s_setprio(1); _Pragma("unroll") for (int m = 0; m < 4; ++m) _Pragma("unroll") for (int n = 0; n < 2; ++n) _Pragma("unroll") for (int k = 0; k < 2; ++k) \
;         acc[ai][bj][m][n] = __builtin_amdgcn_mfma_f32_16x16x32_bf16(Bt[n][k], At[m][k], acc[ai][bj][m][n], 0, 0, 0); __builtin_amdgcn_s_setprio(0); } while (0)
; #define PG8_WAIT_V(n) asm volatile("s_waitcnt vmcnt(" #n ")" ::: "memory")
; #define PG8_WAIT_L(n) asm volatile("s_waitcnt lgkmcnt(" #n ")" ::: "memory")
; #define PG8_BAR __builtin_amdgcn_s_barrier()
; #define PG8_SCHED __builtin_amdgcn_sched_barrier(0)
;     ...
;             PG8_LDA(At, 1, 1); PG8_STAGE(PG8_SB(1, 0), b3, voffB); PG8_STAGE(PG8_SB(1, 1), b3 + hstepB, voffB); PG8_STAGE(PG8_SA(1, 0), a3, voffA);
;             PG8_WAIT_V(8); PG8_WAIT_L(0); PG8_BAR; PG8_MMA(1, 0, At, B0); PG8_MMA(1, 1, At, B1); PG8_BAR; PG8_SCHED;
;         }
	v_mfma_f32_16x16x32_bf16 v[64:67], v[174:177], v[222:225], v[64:67]
	s_setprio 0
	s_add_i32 s26, s68, s31
	v_lshl_add_u64 v[238:239], v[238:239], 0, s[72:73]
	s_mov_b32 m0, s26
	ds_read_b128 v[178:181], v211 offset:49152
	ds_read_b128 v[182:185], v211 offset:50176
	ds_read_b128 v[186:189], v211 offset:51200
	ds_read_b128 v[190:193], v211 offset:52224
	ds_read_b128 v[194:197], v211 offset:53248
	ds_read_b128 v[198:201], v211 offset:54272
	ds_read_b128 v[218:221], v211 offset:55296
	ds_read_b128 v[222:225], v211 offset:56320
	global_load_lds_dwordx4 v[238:239], off
	s_add_i32 m0, s26, 0x2000
	s_add_u32 s24, s24, 0x40080
	v_lshl_add_u64 v[238:239], v[240:241], 0, s[72:73]
	s_addc_u32 s25, s25, 0
	s_add_i32 s26, s69, s31
	global_load_lds_dwordx4 v[238:239], off
	v_lshl_add_u64 v[238:239], s[24:25], 0, v[208:209]
	s_mov_b32 m0, s26
	s_nop 0
	global_load_lds_dwordx4 v[238:239], off
	v_lshl_add_u64 v[238:239], s[24:25], 0, v[156:157]
	s_add_i32 m0, s26, 0x2000
	s_nop 0
	global_load_lds_dwordx4 v[238:239], off
	v_lshl_add_u64 v[238:239], s[20:21], 0, v[160:161]
	s_mov_b32 m0, s47
	s_nop 0
	global_load_lds_dwordx4 v[238:239], off
	v_lshl_add_u64 v[238:239], s[20:21], 0, v[158:159]
	s_mov_b32 m0, s48
	s_nop 0
	global_load_lds_dwordx4 v[238:239], off
	s_waitcnt vmcnt(8)
	s_waitcnt lgkmcnt(0)
	s_barrier
	s_setprio 1
	s_waitcnt lgkmcnt(0)
	v_mfma_f32_16x16x32_bf16 v[60:63], v[132:135], v[178:181], v[60:63]
	v_mfma_f32_16x16x32_bf16 v[56:59], v[140:143], v[178:181], v[56:59]
	v_mfma_f32_16x16x32_bf16 v[44:47], v[132:135], v[186:189], v[44:47]
	v_mfma_f32_16x16x32_bf16 v[40:43], v[140:143], v[186:189], v[40:43]
	v_mfma_f32_16x16x32_bf16 v[28:31], v[132:135], v[194:197], v[28:31]
	v_mfma_f32_16x16x32_bf16 v[24:27], v[140:143], v[194:197], v[24:27]
	v_mfma_f32_16x16x32_bf16 v[12:15], v[132:135], v[218:221], v[12:15]
	v_mfma_f32_16x16x32_bf16 v[8:11], v[140:143], v[218:221], v[8:11]
	v_mfma_f32_16x16x32_bf16 v[60:63], v[136:139], v[182:185], v[60:63]
	v_mfma_f32_16x16x32_bf16 v[56:59], v[144:147], v[182:185], v[56:59]
	v_mfma_f32_16x16x32_bf16 v[44:47], v[136:139], v[190:193], v[44:47]
	v_mfma_f32_16x16x32_bf16 v[40:43], v[144:147], v[190:193], v[40:43]
	v_mfma_f32_16x16x32_bf16 v[28:31], v[136:139], v[198:201], v[28:31]
	v_mfma_f32_16x16x32_bf16 v[24:27], v[144:147], v[198:201], v[24:27]
	v_mfma_f32_16x16x32_bf16 v[12:15], v[136:139], v[222:225], v[12:15]
	v_mfma_f32_16x16x32_bf16 v[8:11], v[144:147], v[222:225], v[8:11]
	s_setprio 0
	s_setprio 1
	v_mfma_f32_16x16x32_bf16 v[52:55], v[148:151], v[178:181], v[52:55]
	v_mfma_f32_16x16x32_bf16 v[48:51], v[170:173], v[178:181], v[48:51]
	v_mfma_f32_16x16x32_bf16 v[36:39], v[148:151], v[186:189], v[36:39]
	v_mfma_f32_16x16x32_bf16 v[32:35], v[170:173], v[186:189], v[32:35]
	v_mfma_f32_16x16x32_bf16 v[20:23], v[148:151], v[194:197], v[20:23]
	v_mfma_f32_16x16x32_bf16 v[16:19], v[170:173], v[194:197], v[16:19]
	v_mfma_f32_16x16x32_bf16 v[4:7], v[148:151], v[218:221], v[4:7]
	v_mfma_f32_16x16x32_bf16 v[0:3], v[170:173], v[218:221], v[0:3]
	v_mfma_f32_16x16x32_bf16 v[52:55], v[152:155], v[182:185], v[52:55]
	v_mfma_f32_16x16x32_bf16 v[48:51], v[174:177], v[182:185], v[48:51]
	v_mfma_f32_16x16x32_bf16 v[36:39], v[152:155], v[190:193], v[36:39]
	v_mfma_f32_16x16x32_bf16 v[32:35], v[174:177], v[190:193], v[32:35]
	v_mfma_f32_16x16x32_bf16 v[20:23], v[152:155], v[198:201], v[20:23]
	v_mfma_f32_16x16x32_bf16 v[16:19], v[174:177], v[198:201], v[16:19]
	v_mfma_f32_16x16x32_bf16 v[4:7], v[152:155], v[222:225], v[4:7]
	s_barrier
	v_mfma_f32_16x16x32_bf16 v[0:3], v[174:177], v[222:225], v[0:3]
	s_setprio 0
	s_add_i32 s67, s67, 2
	s_add_u32 s18, s18, 0x100
	s_addc_u32 s19, s19, 0
	s_cmp_gt_u32 s67, 13
	s_cbranch_scc0 .LBB0_451
	s_branch .Lpeel_exit_451
	.p2alignl 6, 3212836864

;     __device__ __forceinline__ const char* tile(const Unit& u, int t) const { return A + (size_t)u.pm * 2 * hstep() + (size_t)t * (BK * 2); }
;     __device__ __forceinline__ const char* tile(const Unit& u, int t) const { return U + (long)(t >> 2) * xoff + (size_t)u.pn * (1024 * 512) + (size_t)u.pm * 2 * hstep() + (size_t)(t & 3) * (BK * 2); }
; #define PG8_STAGE(bufoff, gbase, voff) do { _Pragma("unroll") for (int _i = 0; _i < 2; ++_i) \
;         __builtin_amdgcn_global_load_lds((const unsigned*)((const char*)(gbase) + (voff)[_i]), (PG8_LAS unsigned*)(lds + (bufoff) + ldsw + _i * 8192), 16, 0, 0); } while (0)
; #define PG8_LDA(dst, b, h) do { _Pragma("unroll") for (int m = 0; m < 4; ++m) _Pragma("unroll") for (int k = 0; k < 2; ++k) dst[m][k] = *(const PG8_LAS bf16x8*)(lds + PG8_SA(b, h) + aoff + m * 2048 + k * 1024); } while (0)
; #define PG8_LDB(dst, b, h) do { _Pragma("unroll") for (int n = 0; n < 2; ++n) _Pragma("unroll") for (int k = 0; k < 2; ++k) dst[n][k] = *(const PG8_LAS bf16x8*)(lds + PG8_SB(b, h) + boff + n * 2048 + k * 1024); } while (0)
; #define PG8_MMA(ai, bj, At, Bt) do { __builtin_amdgcn_s_setprio(1); _Pragma("unroll") for (int m = 0; m < 4; ++m) _Pragma("unroll") for (int n = 0; n < 2; ++n) _Pragma("unroll") for (int k = 0; k < 2; ++k) \
;         acc[ai][bj][m][n] = __builtin_amdgcn_mfma_f32_16x16x32_bf16(Bt[n][k], At[m][k], acc[ai][bj][m][n], 0, 0, 0); __builtin_amdgcn_s_setprio(0); } while (0)
; #define PG8_BAR __builtin_amdgcn_s_barrier()
;     ...
;         for (int t = 0; t < nt; t += 2) {
;             const bool last = (t == nt - 2);
;             const char* a1 = AS.tile(cur, t + 1);
;             const char* a2 = last ? AS.tile(nu, 0) : AS.tile(cur, t + 2); const char* b2 = last ? nB : cB + (size_t)(t + 2) * kstep;
;             const char* a3 = last ? AS.tile(nu, 1) : AS.tile(cur, t + 3); const char* b3 = b2 + kstep;
;             PG8_LDB(B0, 0, 0); PG8_LDB(B1, 0, 1); PG8_SCHED; PG8_LDA(At, 0, 0); PG8_STAGE(PG8_SA(1, 1), a1 + hstepA, voffA);
;             PG8_WAIT_V(8); PG8_WAIT_L(0); PG8_BAR; PG8_MMA(0, 0, At, B0); PG8_MMA(0, 1, At, B1); PG8_BAR; PG8_SCHED;
;             PG8_LDA(At, 0, 1); PG8_STAGE(PG8_SB(0, 0), b2, voffB); PG8_STAGE(PG8_SB(0, 1), b2 + hstepB, voffB); PG8_STAGE(PG8_SA(0, 0), a2, voffA);
;             PG8_WAIT_V(8); PG8_WAIT_L(0); PG8_BAR; PG8_MMA(1, 0, At, B0); PG8_MMA(1, 1, At, B1); PG8_BAR; PG8_SCHED;
.Lpeel_504:
	s_add_u32 s14, s52, s12
	s_addc_u32 s15, s53, s13
	s_add_u32 s18, s14, 0x400100
	s_addc_u32 s19, s15, 0
	s_add_u32 s16, s54, s12
	s_addc_u32 s17, s55, s13
	s_add_u32 s14, s14, 0x400180
	s_addc_u32 s15, s15, 0
	s_add_i32 s57, 0, 0x10000
	s_add_i32 s60, 0, 0x14000
	v_add_u32_e32 v146, s57, v149
	ds_read_b128 v[156:159], v146
	ds_read_b128 v[160:163], v146 offset:1024
	ds_read_b128 v[164:167], v146 offset:2048
	ds_read_b128 v[168:171], v146 offset:3072
	v_add_u32_e32 v146, s60, v149
	ds_read_b128 v[172:175], v146
	ds_read_b128 v[176:179], v146 offset:1024
	ds_read_b128 v[180:183], v146 offset:2048
	ds_read_b128 v[184:187], v146 offset:3072
	s_cmpk_eq_i32 s12, 0x700
	s_cselect_b32 s15, s51, s15
	s_cselect_b32 s14, s50, s14
	s_cselect_b32 s17, s48, s17
	s_cselect_b32 s16, s47, s16
	s_cselect_b32 s19, s49, s19
	s_cselect_b32 s18, s11, s18
	v_lshl_add_u64 v[146:147], v[142:143], 0, s[12:13]
	s_add_i32 m0, s26, 0xc000
	ds_read_b128 v[188:191], v152
	ds_read_b128 v[192:195], v152 offset:1024
	ds_read_b128 v[196:199], v152 offset:2048
	ds_read_b128 v[200:203], v152 offset:3072
	ds_read_b128 v[204:207], v152 offset:4096
	ds_read_b128 v[218:221], v152 offset:5120
	ds_read_b128 v[222:225], v152 offset:6144
	ds_read_b128 v[238:241], v152 offset:7168
	global_load_lds_dwordx4 v[146:147], off
	v_lshl_add_u64 v[146:147], v[144:145], 0, s[12:13]
	s_add_i32 m0, s26, 0xe000
	s_nop 0
	global_load_lds_dwordx4 v[146:147], off
	s_waitcnt vmcnt(24)
	s_waitcnt lgkmcnt(0)
	s_barrier
	s_setprio 1
	s_waitcnt lgkmcnt(0)
	v_mfma_f32_16x16x32_bf16 v[124:127], v[156:159], v[188:191], 0
	v_mfma_f32_16x16x32_bf16 v[120:123], v[164:167], v[188:191], 0
	v_mfma_f32_16x16x32_bf16 v[108:111], v[156:159], v[196:199], 0
	v_mfma_f32_16x16x32_bf16 v[104:107], v[164:167], v[196:199], 0
	v_mfma_f32_16x16x32_bf16 v[92:95], v[156:159], v[204:207], 0
	v_mfma_f32_16x16x32_bf16 v[88:91], v[164:167], v[204:207], 0
	v_mfma_f32_16x16x32_bf16 v[76:79], v[156:159], v[222:225], 0
	v_mfma_f32_16x16x32_bf16 v[72:75], v[164:167], v[222:225], 0
	v_mfma_f32_16x16x32_bf16 v[124:127], v[160:163], v[192:195], v[124:127]
	v_mfma_f32_16x16x32_bf16 v[120:123], v[168:171], v[192:195], v[120:123]
	v_mfma_f32_16x16x32_bf16 v[108:111], v[160:163], v[200:203], v[108:111]
	v_mfma_f32_16x16x32_bf16 v[104:107], v[168:171], v[200:203], v[104:107]
	v_mfma_f32_16x16x32_bf16 v[92:95], v[160:163], v[218:221], v[92:95]
	v_mfma_f32_16x16x32_bf16 v[88:91], v[168:171], v[218:221], v[88:91]
	v_mfma_f32_16x16x32_bf16 v[76:79], v[160:163], v[238:241], v[76:79]
	v_mfma_f32_16x16x32_bf16 v[72:75], v[168:171], v[238:241], v[72:75]
	s_setprio 0
	s_setprio 1
	v_mfma_f32_16x16x32_bf16 v[116:119], v[172:175], v[188:191], 0
	v_mfma_f32_16x16x32_bf16 v[112:115], v[180:183], v[188:191], 0
	v_mfma_f32_16x16x32_bf16 v[100:103], v[172:175], v[196:199], 0
	v_mfma_f32_16x16x32_bf16 v[96:99], v[180:183], v[196:199], 0
	v_mfma_f32_16x16x32_bf16 v[84:87], v[172:175], v[204:207], 0
	v_mfma_f32_16x16x32_bf16 v[80:83], v[180:183], v[204:207], 0
	v_mfma_f32_16x16x32_bf16 v[68:71], v[172:175], v[222:225], 0
	v_mfma_f32_16x16x32_bf16 v[64:67], v[180:183], v[222:225], 0
	v_mfma_f32_16x16x32_bf16 v[116:119], v[176:179], v[192:195], v[116:119]
	v_mfma_f32_16x16x32_bf16 v[112:115], v[184:187], v[192:195], v[112:115]
	v_mfma_f32_16x16x32_bf16 v[100:103], v[176:179], v[200:203], v[100:103]
	v_mfma_f32_16x16x32_bf16 v[96:99], v[184:187], v[200:203], v[96:99]
	v_mfma_f32_16x16x32_bf16 v[84:87], v[176:179], v[218:221], v[84:87]
	v_mfma_f32_16x16x32_bf16 v[80:83], v[184:187], v[218:221], v[80:83]
	v_mfma_f32_16x16x32_bf16 v[68:71], v[176:179], v[238:241], v[68:71]
	s_barrier
	v_mfma_f32_16x16x32_bf16 v[64:67], v[184:187], v[238:241], v[64:67]
	s_setprio 0
	s_add_i32 s57, s57, s25
	v_lshl_add_u64 v[146:147], s[16:17], 0, v[208:209]
	s_mov_b32 m0, s57
	ds_read_b128 v[188:191], v152 offset:16384
	ds_read_b128 v[192:195], v152 offset:17408
	ds_read_b128 v[196:199], v152 offset:18432
	ds_read_b128 v[200:203], v152 offset:19456
	ds_read_b128 v[204:207], v152 offset:20480
	ds_read_b128 v[218:221], v152 offset:21504
	ds_read_b128 v[222:225], v152 offset:22528
	ds_read_b128 v[238:241], v152 offset:23552
	global_load_lds_dwordx4 v[146:147], off
	s_add_i32 m0, s57, 0x2000
	s_add_u32 s58, s16, 0x40000
	v_lshl_add_u64 v[242:243], s[16:17], 0, v[128:129]
	s_addc_u32 s59, s17, 0
	s_add_i32 s57, s60, s25
	global_load_lds_dwordx4 v[242:243], off
	v_lshl_add_u64 v[244:245], s[58:59], 0, v[208:209]
	s_mov_b32 m0, s57
	s_nop 0
	global_load_lds_dwordx4 v[244:245], off
	v_lshl_add_u64 v[244:245], s[58:59], 0, v[128:129]
	s_add_i32 m0, s57, 0x2000
	s_nop 0
	global_load_lds_dwordx4 v[244:245], off
	v_lshl_add_u64 v[244:245], s[18:19], 0, v[132:133]
	s_mov_b32 m0, s26
	s_nop 0
	global_load_lds_dwordx4 v[244:245], off
	v_lshl_add_u64 v[244:245], s[18:19], 0, v[130:131]
	s_mov_b32 m0, s27
	s_nop 0
	global_load_lds_dwordx4 v[244:245], off
	s_waitcnt vmcnt(8)
	s_waitcnt lgkmcnt(0)
	s_barrier
; #define PG8_STAGE(bufoff, gbase, voff) do { _Pragma("unroll") for (int _i = 0; _i < 2; ++_i) \
;         __builtin_amdgcn_global_load_lds((const unsigned*)((const char*)(gbase) + (voff)[_i]), (PG8_LAS unsigned*)(lds + (bufoff) + ldsw + _i * 8192), 16, 0, 0); } while (0)
; #define PG8_LDA(dst, b, h) do { _Pragma("unroll") for (int m = 0; m < 4; ++m) _Pragma("unroll") for (int k = 0; k < 2; ++k) dst[m][k] = *(const PG8_LAS bf16x8*)(lds + PG8_SA(b, h) + aoff + m * 2048 + k * 1024); } while (0)
; #define PG8_LDB(dst, b, h) do { _Pragma("unroll") for (int n = 0; n < 2; ++n) _Pragma("unroll") for (int k = 0; k < 2; ++k) dst[n][k] = *(const PG8_LAS bf16x8*)(lds + PG8_SB(b, h) + boff + n * 2048 + k * 1024); } while (0)
; #define PG8_MMA(ai, bj, At, Bt) do { __builtin_amdgcn_s_setprio(1); _Pragma("unroll") for (int m = 0; m < 4; ++m) _Pragma("unroll") for (int n = 0; n < 2; ++n) _Pragma("unroll") for (int k = 0; k < 2; ++k) \
;         acc[ai][bj][m][n] = __builtin_amdgcn_mfma_f32_16x16x32_bf16(Bt[n][k], At[m][k], acc[ai][bj][m][n], 0, 0, 0); __builtin_amdgcn_s_setprio(0); } while (0)
; #define PG8_WAIT_V(n) asm volatile("s_waitcnt vmcnt(" #n ")" ::: "memory")
; #define PG8_WAIT_L(n) asm volatile("s_waitcnt lgkmcnt(" #n ")" ::: "memory")
; #define PG8_BAR __builtin_amdgcn_s_barrier()
; #define PG8_SCHED __builtin_amdgcn_sched_barrier(0)
;     ...
;             PG8_WAIT_V(8); PG8_WAIT_L(0); PG8_BAR; PG8_MMA(1, 0, At, B0); PG8_MMA(1, 1, At, B1); PG8_BAR; PG8_SCHED;
;             PG8_LDB(B0, 1, 0); PG8_LDB(B1, 1, 1); PG8_SCHED; PG8_LDA(At, 1, 0); PG8_STAGE(PG8_SA(0, 1), a2 + hstepA, voffA);
;             PG8_WAIT_V(8); PG8_WAIT_L(0); PG8_BAR; PG8_MMA(0, 0, At, B0); PG8_MMA(0, 1, At, B1); PG8_BAR; PG8_SCHED;
;             PG8_LDA(At, 1, 1); PG8_STAGE(PG8_SB(1, 0), b3, voffB); PG8_STAGE(PG8_SB(1, 1), b3 + hstepB, voffB); PG8_STAGE(PG8_SA(1, 0), a3, voffA);
	s_setprio 1
	s_waitcnt lgkmcnt(0)
	v_mfma_f32_16x16x32_bf16 v[60:63], v[156:159], v[188:191], 0
	v_mfma_f32_16x16x32_bf16 v[56:59], v[164:167], v[188:191], 0
	v_mfma_f32_16x16x32_bf16 v[44:47], v[156:159], v[196:199], 0
	v_mfma_f32_16x16x32_bf16 v[40:43], v[164:167], v[196:199], 0
	v_mfma_f32_16x16x32_bf16 v[28:31], v[156:159], v[204:207], 0
	v_mfma_f32_16x16x32_bf16 v[24:27], v[164:167], v[204:207], 0
	v_mfma_f32_16x16x32_bf16 v[12:15], v[156:159], v[222:225], 0
	v_mfma_f32_16x16x32_bf16 v[8:11], v[164:167], v[222:225], 0
	v_mfma_f32_16x16x32_bf16 v[60:63], v[160:163], v[192:195], v[60:63]
	v_mfma_f32_16x16x32_bf16 v[56:59], v[168:171], v[192:195], v[56:59]
	v_mfma_f32_16x16x32_bf16 v[44:47], v[160:163], v[200:203], v[44:47]
	v_mfma_f32_16x16x32_bf16 v[40:43], v[168:171], v[200:203], v[40:43]
	v_mfma_f32_16x16x32_bf16 v[28:31], v[160:163], v[218:221], v[28:31]
	v_mfma_f32_16x16x32_bf16 v[24:27], v[168:171], v[218:221], v[24:27]
	v_mfma_f32_16x16x32_bf16 v[12:15], v[160:163], v[238:241], v[12:15]
	v_mfma_f32_16x16x32_bf16 v[8:11], v[168:171], v[238:241], v[8:11]
	s_setprio 0
	s_setprio 1
	v_mfma_f32_16x16x32_bf16 v[52:55], v[172:175], v[188:191], 0
	v_mfma_f32_16x16x32_bf16 v[48:51], v[180:183], v[188:191], 0
	v_mfma_f32_16x16x32_bf16 v[36:39], v[172:175], v[196:199], 0
	v_mfma_f32_16x16x32_bf16 v[32:35], v[180:183], v[196:199], 0
	v_mfma_f32_16x16x32_bf16 v[20:23], v[172:175], v[204:207], 0
	v_mfma_f32_16x16x32_bf16 v[16:19], v[180:183], v[204:207], 0
	v_mfma_f32_16x16x32_bf16 v[4:7], v[172:175], v[222:225], 0
	v_mfma_f32_16x16x32_bf16 v[0:3], v[180:183], v[222:225], 0
	v_mfma_f32_16x16x32_bf16 v[52:55], v[176:179], v[192:195], v[52:55]
	v_mfma_f32_16x16x32_bf16 v[48:51], v[184:187], v[192:195], v[48:51]
	v_mfma_f32_16x16x32_bf16 v[36:39], v[176:179], v[200:203], v[36:39]
	v_mfma_f32_16x16x32_bf16 v[32:35], v[184:187], v[200:203], v[32:35]
	v_mfma_f32_16x16x32_bf16 v[20:23], v[176:179], v[218:221], v[20:23]
	v_mfma_f32_16x16x32_bf16 v[16:19], v[184:187], v[218:221], v[16:19]
	v_mfma_f32_16x16x32_bf16 v[4:7], v[176:179], v[238:241], v[4:7]
	s_barrier
	v_mfma_f32_16x16x32_bf16 v[0:3], v[184:187], v[238:241], v[0:3]
	s_setprio 0
	s_add_i32 s57, 0, 0x18000
	v_add_u32_e32 v155, s57, v149
	s_add_i32 s58, 0, 0x1c000
	ds_read_b128 v[156:159], v155
	ds_read_b128 v[160:163], v155 offset:1024
	ds_read_b128 v[164:167], v155 offset:2048
	ds_read_b128 v[168:171], v155 offset:3072
	v_add_u32_e32 v155, s58, v149
	ds_read_b128 v[172:175], v155
	ds_read_b128 v[176:179], v155 offset:1024
	ds_read_b128 v[180:183], v155 offset:2048
	ds_read_b128 v[184:187], v155 offset:3072
	s_add_u32 s18, s18, 0x40000
	s_addc_u32 s19, s19, 0
	s_mov_b32 m0, s28
	v_lshl_add_u64 v[244:245], s[18:19], 0, v[132:133]
	ds_read_b128 v[188:191], v152 offset:32768
	ds_read_b128 v[192:195], v152 offset:33792
	ds_read_b128 v[196:199], v152 offset:34816
	ds_read_b128 v[200:203], v152 offset:35840
	ds_read_b128 v[204:207], v152 offset:36864
	ds_read_b128 v[218:221], v152 offset:37888
	ds_read_b128 v[222:225], v152 offset:38912
	ds_read_b128 v[238:241], v152 offset:39936
	global_load_lds_dwordx4 v[244:245], off
	v_lshl_add_u64 v[244:245], s[18:19], 0, v[130:131]
	s_mov_b32 m0, s29
	s_nop 0
	global_load_lds_dwordx4 v[244:245], off
	s_waitcnt vmcnt(8)
	s_waitcnt lgkmcnt(0)
	s_barrier
	s_setprio 1
	s_waitcnt lgkmcnt(0)
	v_mfma_f32_16x16x32_bf16 v[124:127], v[156:159], v[188:191], v[124:127]
	v_mfma_f32_16x16x32_bf16 v[120:123], v[164:167], v[188:191], v[120:123]
	v_mfma_f32_16x16x32_bf16 v[108:111], v[156:159], v[196:199], v[108:111]
	v_mfma_f32_16x16x32_bf16 v[104:107], v[164:167], v[196:199], v[104:107]
	v_mfma_f32_16x16x32_bf16 v[92:95], v[156:159], v[204:207], v[92:95]
	v_mfma_f32_16x16x32_bf16 v[88:91], v[164:167], v[204:207], v[88:91]
	v_mfma_f32_16x16x32_bf16 v[76:79], v[156:159], v[222:225], v[76:79]
	v_mfma_f32_16x16x32_bf16 v[72:75], v[164:167], v[222:225], v[72:75]
	v_mfma_f32_16x16x32_bf16 v[124:127], v[160:163], v[192:195], v[124:127]
	v_mfma_f32_16x16x32_bf16 v[120:123], v[168:171], v[192:195], v[120:123]
	v_mfma_f32_16x16x32_bf16 v[108:111], v[160:163], v[200:203], v[108:111]
	v_mfma_f32_16x16x32_bf16 v[104:107], v[168:171], v[200:203], v[104:107]
	v_mfma_f32_16x16x32_bf16 v[92:95], v[160:163], v[218:221], v[92:95]
	v_mfma_f32_16x16x32_bf16 v[88:91], v[168:171], v[218:221], v[88:91]
	v_mfma_f32_16x16x32_bf16 v[76:79], v[160:163], v[238:241], v[76:79]
	v_mfma_f32_16x16x32_bf16 v[72:75], v[168:171], v[238:241], v[72:75]
	s_setprio 0
	s_setprio 1
	v_mfma_f32_16x16x32_bf16 v[116:119], v[172:175], v[188:191], v[116:119]
	v_mfma_f32_16x16x32_bf16 v[112:115], v[180:183], v[188:191], v[112:115]
	v_mfma_f32_16x16x32_bf16 v[100:103], v[172:175], v[196:199], v[100:103]
	v_mfma_f32_16x16x32_bf16 v[96:99], v[180:183], v[196:199], v[96:99]
	v_mfma_f32_16x16x32_bf16 v[84:87], v[172:175], v[204:207], v[84:87]
	v_mfma_f32_16x16x32_bf16 v[80:83], v[180:183], v[204:207], v[80:83]
	v_mfma_f32_16x16x32_bf16 v[68:71], v[172:175], v[222:225], v[68:71]
	v_mfma_f32_16x16x32_bf16 v[64:67], v[180:183], v[222:225], v[64:67]
	v_mfma_f32_16x16x32_bf16 v[116:119], v[176:179], v[192:195], v[116:119]
	v_mfma_f32_16x16x32_bf16 v[112:115], v[184:187], v[192:195], v[112:115]
	v_mfma_f32_16x16x32_bf16 v[100:103], v[176:179], v[200:203], v[100:103]
	v_mfma_f32_16x16x32_bf16 v[96:99], v[184:187], v[200:203], v[96:99]
	v_mfma_f32_16x16x32_bf16 v[84:87], v[176:179], v[218:221], v[84:87]
	v_mfma_f32_16x16x32_bf16 v[80:83], v[184:187], v[218:221], v[80:83]
	v_mfma_f32_16x16x32_bf16 v[68:71], v[176:179], v[238:241], v[68:71]
	s_barrier
; #define PG8_STAGE(bufoff, gbase, voff) do { _Pragma("unroll") for (int _i = 0; _i < 2; ++_i) \
;         __builtin_amdgcn_global_load_lds((const unsigned*)((const char*)(gbase) + (voff)[_i]), (PG8_LAS unsigned*)(lds + (bufoff) + ldsw + _i * 8192), 16, 0, 0); } while (0)
; #define PG8_LDA(dst, b, h) do { _Pragma("unroll") for (int m = 0; m < 4; ++m) _Pragma("unroll") for (int k = 0; k < 2; ++k) dst[m][k] = *(const PG8_LAS bf16x8*)(lds + PG8_SA(b, h) + aoff + m * 2048 + k * 1024); } while (0)
; #define PG8_MMA(ai, bj, At, Bt) do { __builtin_amdgcn_s_setprio(1); _Pragma("unroll") for (int m = 0; m < 4; ++m) _Pragma("unroll") for (int n = 0; n < 2; ++n) _Pragma("unroll") for (int k = 0; k < 2; ++k) \
;         acc[ai][bj][m][n] = __builtin_amdgcn_mfma_f32_16x16x32_bf16(Bt[n][k], At[m][k], acc[ai][bj][m][n], 0, 0, 0); __builtin_amdgcn_s_setprio(0); } while (0)
; #define PG8_WAIT_V(n) asm volatile("s_waitcnt vmcnt(" #n ")" ::: "memory")
; #define PG8_WAIT_L(n) asm volatile("s_waitcnt lgkmcnt(" #n ")" ::: "memory")
; #define PG8_BAR __builtin_amdgcn_s_barrier()
; #define PG8_SCHED __builtin_amdgcn_sched_barrier(0)
;     ...
;             PG8_LDA(At, 1, 1); PG8_STAGE(PG8_SB(1, 0), b3, voffB); PG8_STAGE(PG8_SB(1, 1), b3 + hstepB, voffB); PG8_STAGE(PG8_SA(1, 0), a3, voffA);
;             PG8_WAIT_V(8); PG8_WAIT_L(0); PG8_BAR; PG8_MMA(1, 0, At, B0); PG8_MMA(1, 1, At, B1); PG8_BAR; PG8_SCHED;
;         }
	v_mfma_f32_16x16x32_bf16 v[64:67], v[184:187], v[238:241], v[64:67]
	s_setprio 0
	s_add_i32 s18, s57, s25
	v_lshl_add_u64 v[146:147], v[146:147], 0, s[64:65]
	s_mov_b32 m0, s18
	ds_read_b128 v[188:191], v152 offset:49152
	ds_read_b128 v[192:195], v152 offset:50176
	ds_read_b128 v[196:199], v152 offset:51200
	ds_read_b128 v[200:203], v152 offset:52224
	ds_read_b128 v[204:207], v152 offset:53248
	ds_read_b128 v[218:221], v152 offset:54272
	ds_read_b128 v[222:225], v152 offset:55296
	ds_read_b128 v[238:241], v152 offset:56320
	global_load_lds_dwordx4 v[146:147], off
	s_add_i32 m0, s18, 0x2000
	s_add_u32 s16, s16, 0x40080
	v_lshl_add_u64 v[146:147], v[242:243], 0, s[64:65]
	s_addc_u32 s17, s17, 0
	s_add_i32 s18, s58, s25
	global_load_lds_dwordx4 v[146:147], off
	v_lshl_add_u64 v[146:147], s[16:17], 0, v[208:209]
	s_mov_b32 m0, s18
	s_nop 0
	global_load_lds_dwordx4 v[146:147], off
	v_lshl_add_u64 v[146:147], s[16:17], 0, v[128:129]
	s_add_i32 m0, s18, 0x2000
	s_nop 0
	global_load_lds_dwordx4 v[146:147], off
	v_lshl_add_u64 v[146:147], s[14:15], 0, v[132:133]
	s_mov_b32 m0, s30
	s_nop 0
	global_load_lds_dwordx4 v[146:147], off
	v_lshl_add_u64 v[146:147], s[14:15], 0, v[130:131]
	s_mov_b32 m0, s31
	s_nop 0
	global_load_lds_dwordx4 v[146:147], off
	s_waitcnt vmcnt(8)
	s_waitcnt lgkmcnt(0)
	s_barrier
	s_setprio 1
	s_waitcnt lgkmcnt(0)
	v_mfma_f32_16x16x32_bf16 v[60:63], v[156:159], v[188:191], v[60:63]
	v_mfma_f32_16x16x32_bf16 v[56:59], v[164:167], v[188:191], v[56:59]
	v_mfma_f32_16x16x32_bf16 v[44:47], v[156:159], v[196:199], v[44:47]
	v_mfma_f32_16x16x32_bf16 v[40:43], v[164:167], v[196:199], v[40:43]
	v_mfma_f32_16x16x32_bf16 v[28:31], v[156:159], v[204:207], v[28:31]
	v_mfma_f32_16x16x32_bf16 v[24:27], v[164:167], v[204:207], v[24:27]
	v_mfma_f32_16x16x32_bf16 v[12:15], v[156:159], v[222:225], v[12:15]
	v_mfma_f32_16x16x32_bf16 v[8:11], v[164:167], v[222:225], v[8:11]
	v_mfma_f32_16x16x32_bf16 v[60:63], v[160:163], v[192:195], v[60:63]
	v_mfma_f32_16x16x32_bf16 v[56:59], v[168:171], v[192:195], v[56:59]
	v_mfma_f32_16x16x32_bf16 v[44:47], v[160:163], v[200:203], v[44:47]
	v_mfma_f32_16x16x32_bf16 v[40:43], v[168:171], v[200:203], v[40:43]
	v_mfma_f32_16x16x32_bf16 v[28:31], v[160:163], v[218:221], v[28:31]
	v_mfma_f32_16x16x32_bf16 v[24:27], v[168:171], v[218:221], v[24:27]
	v_mfma_f32_16x16x32_bf16 v[12:15], v[160:163], v[238:241], v[12:15]
	v_mfma_f32_16x16x32_bf16 v[8:11], v[168:171], v[238:241], v[8:11]
	s_setprio 0
	s_setprio 1
	v_mfma_f32_16x16x32_bf16 v[52:55], v[172:175], v[188:191], v[52:55]
	v_mfma_f32_16x16x32_bf16 v[48:51], v[180:183], v[188:191], v[48:51]
	v_mfma_f32_16x16x32_bf16 v[36:39], v[172:175], v[196:199], v[36:39]
	v_mfma_f32_16x16x32_bf16 v[32:35], v[180:183], v[196:199], v[32:35]
	v_mfma_f32_16x16x32_bf16 v[20:23], v[172:175], v[204:207], v[20:23]
	v_mfma_f32_16x16x32_bf16 v[16:19], v[180:183], v[204:207], v[16:19]
	v_mfma_f32_16x16x32_bf16 v[4:7], v[172:175], v[222:225], v[4:7]
	v_mfma_f32_16x16x32_bf16 v[0:3], v[180:183], v[222:225], v[0:3]
	v_mfma_f32_16x16x32_bf16 v[52:55], v[176:179], v[192:195], v[52:55]
	v_mfma_f32_16x16x32_bf16 v[48:51], v[184:187], v[192:195], v[48:51]
	v_mfma_f32_16x16x32_bf16 v[36:39], v[176:179], v[200:203], v[36:39]
	v_mfma_f32_16x16x32_bf16 v[32:35], v[184:187], v[200:203], v[32:35]
	v_mfma_f32_16x16x32_bf16 v[20:23], v[176:179], v[218:221], v[20:23]
	v_mfma_f32_16x16x32_bf16 v[16:19], v[184:187], v[218:221], v[16:19]
	v_mfma_f32_16x16x32_bf16 v[4:7], v[176:179], v[238:241], v[4:7]
	s_barrier
	v_mfma_f32_16x16x32_bf16 v[0:3], v[184:187], v[238:241], v[0:3]
	s_setprio 0
	s_add_i32 s56, s56, 2
	s_add_u32 s12, s12, 0x100
	s_addc_u32 s13, s13, 0
	s_cmp_gt_u32 s56, 13
	s_cbranch_scc0 .LBB0_504
	s_branch .Lpeel_exit_504
	.p2alignl 6, 3212836864

;     __device__ __forceinline__ const char* tile(const Unit& u, int t) const { return A + (size_t)u.pm * 2 * hstep() + (size_t)t * (BK * 2); }
;     __device__ __forceinline__ const char* tile(const Unit& u, int t) const { return U + (long)(t >> 2) * xoff + (size_t)u.pn * (1024 * 512) + (size_t)u.pm * 2 * hstep() + (size_t)(t & 3) * (BK * 2); }
; #define PG8_STAGE(bufoff, gbase, voff) do { _Pragma("unroll") for (int _i = 0; _i < 2; ++_i) \
;         __builtin_amdgcn_global_load_lds((const unsigned*)((const char*)(gbase) + (voff)[_i]), (PG8_LAS unsigned*)(lds + (bufoff) + ldsw + _i * 8192), 16, 0, 0); } while (0)
; #define PG8_LDA(dst, b, h) do { _Pragma("unroll") for (int m = 0; m < 4; ++m) _Pragma("unroll") for (int k = 0; k < 2; ++k) dst[m][k] = *(const PG8_LAS bf16x8*)(lds + PG8_SA(b, h) + aoff + m * 2048 + k * 1024); } while (0)
; #define PG8_LDB(dst, b, h) do { _Pragma("unroll") for (int n = 0; n < 2; ++n) _Pragma("unroll") for (int k = 0; k < 2; ++k) dst[n][k] = *(const PG8_LAS bf16x8*)(lds + PG8_SB(b, h) + boff + n * 2048 + k * 1024); } while (0)
; #define PG8_MMA(ai, bj, At, Bt) do { __builtin_amdgcn_s_setprio(1); _Pragma("unroll") for (int m = 0; m < 4; ++m) _Pragma("unroll") for (int n = 0; n < 2; ++n) _Pragma("unroll") for (int k = 0; k < 2; ++k) \
;         acc[ai][bj][m][n] = __builtin_amdgcn_mfma_f32_16x16x32_bf16(Bt[n][k], At[m][k], acc[ai][bj][m][n], 0, 0, 0); __builtin_amdgcn_s_setprio(0); } while (0)
; #define PG8_BAR __builtin_amdgcn_s_barrier()
;     ...
;         for (int t = 0; t < nt; t += 2) {
;             const bool last = (t == nt - 2);
;             const char* a1 = AS.tile(cur, t + 1);
;             const char* a2 = last ? AS.tile(nu, 0) : AS.tile(cur, t + 2); const char* b2 = last ? nB : cB + (size_t)(t + 2) * kstep;
;             const char* a3 = last ? AS.tile(nu, 1) : AS.tile(cur, t + 3); const char* b3 = b2 + kstep;
;             PG8_LDB(B0, 0, 0); PG8_LDB(B1, 0, 1); PG8_SCHED; PG8_LDA(At, 0, 0); PG8_STAGE(PG8_SA(1, 1), a1 + hstepA, voffA);
;             PG8_WAIT_V(8); PG8_WAIT_L(0); PG8_BAR; PG8_MMA(0, 0, At, B0); PG8_MMA(0, 1, At, B1); PG8_BAR; PG8_SCHED;
;             PG8_LDA(At, 0, 1); PG8_STAGE(PG8_SB(0, 0), b2, voffB); PG8_STAGE(PG8_SB(0, 1), b2 + hstepB, voffB); PG8_STAGE(PG8_SA(0, 0), a2, voffA);
;             PG8_WAIT_V(8); PG8_WAIT_L(0); PG8_BAR; PG8_MMA(1, 0, At, B0); PG8_MMA(1, 1, At, B1); PG8_BAR; PG8_SCHED;
.Lpeel_534:
	s_add_i32 s68, s2, 2
	s_add_u32 s3, s82, s64
	s_addc_u32 s20, s83, s65
	s_add_u32 s69, s3, 0x100
	s_addc_u32 s21, s20, 0
	s_add_u32 s70, s82, s66
	s_addc_u32 s71, s83, s67
	s_add_u32 s72, s3, 0x180
	s_addc_u32 s3, s20, 0
	s_add_i32 s73, 0, 0x10000
	s_add_i32 s74, 0, 0x14000
	v_add_u32_e32 v108, s73, v212
	v_add_u32_e32 v152, s74, v212
	ds_read_b128 v[76:79], v108
	ds_read_b128 v[88:91], v108 offset:1024
	ds_read_b128 v[100:103], v108 offset:2048
	ds_read_b128 v[108:111], v108 offset:3072
	ds_read_b128 v[124:127], v152
	ds_read_b128 v[128:131], v152 offset:1024
	ds_read_b128 v[144:147], v152 offset:2048
	ds_read_b128 v[152:155], v152 offset:3072
	s_cmp_eq_u32 s51, s2
	s_cselect_b32 s2, s60, s72
	s_cselect_b32 s3, s61, s3
	s_cselect_b32 s71, s41, s71
	s_cselect_b32 s70, s40, s70
	s_cselect_b32 s21, s59, s21
	s_cselect_b32 s20, s1, s69
	v_lshl_add_u64 v[222:223], s[82:83], 0, v[64:65]
	s_add_i32 m0, s35, 0xc000
	ds_read_b128 v[156:159], v241
	ds_read_b128 v[168:171], v241 offset:1024
	ds_read_b128 v[172:175], v241 offset:2048
	ds_read_b128 v[176:179], v241 offset:3072
	ds_read_b128 v[180:183], v241 offset:4096
	ds_read_b128 v[184:187], v241 offset:5120
	ds_read_b128 v[188:191], v241 offset:6144
	ds_read_b128 v[218:221], v241 offset:7168
	global_load_lds_dwordx4 v[222:223], off
	v_lshl_add_u64 v[222:223], s[82:83], 0, v[66:67]
	s_add_i32 m0, s35, 0xe000
	s_nop 0
	global_load_lds_dwordx4 v[222:223], off
	s_waitcnt vmcnt(8)
	s_waitcnt lgkmcnt(0)
	s_barrier
	s_setprio 1
	s_waitcnt lgkmcnt(0)
	v_mfma_f32_16x16x32_bf16 v[164:167], v[76:79], v[156:159], 0
	v_mfma_f32_16x16x32_bf16 v[160:163], v[100:103], v[156:159], 0
	v_mfma_f32_16x16x32_bf16 v[136:139], v[76:79], v[172:175], 0
	v_mfma_f32_16x16x32_bf16 v[132:135], v[100:103], v[172:175], 0
	v_mfma_f32_16x16x32_bf16 v[112:115], v[76:79], v[180:183], 0
	v_mfma_f32_16x16x32_bf16 v[104:107], v[100:103], v[180:183], 0
	v_mfma_f32_16x16x32_bf16 v[84:87], v[76:79], v[188:191], 0
	v_mfma_f32_16x16x32_bf16 v[80:83], v[100:103], v[188:191], 0
	v_mfma_f32_16x16x32_bf16 v[164:167], v[88:91], v[168:171], v[164:167]
	v_mfma_f32_16x16x32_bf16 v[160:163], v[108:111], v[168:171], v[160:163]
	v_mfma_f32_16x16x32_bf16 v[136:139], v[88:91], v[176:179], v[136:139]
	v_mfma_f32_16x16x32_bf16 v[132:135], v[108:111], v[176:179], v[132:135]
	v_mfma_f32_16x16x32_bf16 v[112:115], v[88:91], v[184:187], v[112:115]
	v_mfma_f32_16x16x32_bf16 v[104:107], v[108:111], v[184:187], v[104:107]
	v_mfma_f32_16x16x32_bf16 v[84:87], v[88:91], v[218:221], v[84:87]
	v_mfma_f32_16x16x32_bf16 v[80:83], v[108:111], v[218:221], v[80:83]
	s_setprio 0
	s_setprio 1
	v_mfma_f32_16x16x32_bf16 v[148:151], v[124:127], v[156:159], 0
	v_mfma_f32_16x16x32_bf16 v[140:143], v[144:147], v[156:159], 0
	v_mfma_f32_16x16x32_bf16 v[120:123], v[124:127], v[172:175], 0
	v_mfma_f32_16x16x32_bf16 v[116:119], v[144:147], v[172:175], 0
	v_mfma_f32_16x16x32_bf16 v[96:99], v[124:127], v[180:183], 0
	v_mfma_f32_16x16x32_bf16 v[92:95], v[144:147], v[180:183], 0
	v_mfma_f32_16x16x32_bf16 v[72:75], v[124:127], v[188:191], 0
	v_mfma_f32_16x16x32_bf16 v[68:71], v[144:147], v[188:191], 0
	v_mfma_f32_16x16x32_bf16 v[148:151], v[128:131], v[168:171], v[148:151]
	v_mfma_f32_16x16x32_bf16 v[140:143], v[152:155], v[168:171], v[140:143]
	v_mfma_f32_16x16x32_bf16 v[120:123], v[128:131], v[176:179], v[120:123]
	v_mfma_f32_16x16x32_bf16 v[116:119], v[152:155], v[176:179], v[116:119]
	v_mfma_f32_16x16x32_bf16 v[96:99], v[128:131], v[184:187], v[96:99]
	v_mfma_f32_16x16x32_bf16 v[92:95], v[152:155], v[184:187], v[92:95]
	v_mfma_f32_16x16x32_bf16 v[72:75], v[128:131], v[218:221], v[72:75]
	s_barrier
	v_mfma_f32_16x16x32_bf16 v[68:71], v[152:155], v[218:221], v[68:71]
	s_setprio 0
	s_add_i32 s69, s73, s25
	v_lshl_add_u64 v[222:223], s[70:71], 0, v[196:197]
	s_mov_b32 m0, s69
	ds_read_b128 v[156:159], v241 offset:16384
	ds_read_b128 v[168:171], v241 offset:17408
	ds_read_b128 v[172:175], v241 offset:18432
	ds_read_b128 v[176:179], v241 offset:19456
	ds_read_b128 v[180:183], v241 offset:20480
	ds_read_b128 v[184:187], v241 offset:21504
	ds_read_b128 v[188:191], v241 offset:22528
	ds_read_b128 v[218:221], v241 offset:23552
	global_load_lds_dwordx4 v[222:223], off
	s_add_i32 m0, s69, 0x2000
	v_lshl_add_u64 v[224:225], s[70:71], 0, v[192:193]
	s_add_u32 s70, s70, s24
	s_addc_u32 s71, s71, 0
	s_add_i32 s69, s74, s25
	global_load_lds_dwordx4 v[224:225], off
	v_lshl_add_u64 v[244:245], s[70:71], 0, v[196:197]
	s_mov_b32 m0, s69
	v_lshl_add_u64 v[246:247], s[70:71], 0, v[192:193]
	global_load_lds_dwordx4 v[244:245], off
	s_add_i32 m0, s69, 0x2000
	v_lshl_add_u64 v[248:249], s[20:21], 0, v[198:199]
	global_load_lds_dwordx4 v[246:247], off
	s_mov_b32 m0, s35
	s_nop 0
	global_load_lds_dwordx4 v[248:249], off
	v_lshl_add_u64 v[248:249], s[20:21], 0, v[194:195]
	s_mov_b32 m0, s44
	s_nop 0
	global_load_lds_dwordx4 v[248:249], off
	s_waitcnt vmcnt(8)
	s_waitcnt lgkmcnt(0)
	s_barrier
; #define PG8_STAGE(bufoff, gbase, voff) do { _Pragma("unroll") for (int _i = 0; _i < 2; ++_i) \
;         __builtin_amdgcn_global_load_lds((const unsigned*)((const char*)(gbase) + (voff)[_i]), (PG8_LAS unsigned*)(lds + (bufoff) + ldsw + _i * 8192), 16, 0, 0); } while (0)
; #define PG8_LDA(dst, b, h) do { _Pragma("unroll") for (int m = 0; m < 4; ++m) _Pragma("unroll") for (int k = 0; k < 2; ++k) dst[m][k] = *(const PG8_LAS bf16x8*)(lds + PG8_SA(b, h) + aoff + m * 2048 + k * 1024); } while (0)
; #define PG8_LDB(dst, b, h) do { _Pragma("unroll") for (int n = 0; n < 2; ++n) _Pragma("unroll") for (int k = 0; k < 2; ++k) dst[n][k] = *(const PG8_LAS bf16x8*)(lds + PG8_SB(b, h) + boff + n * 2048 + k * 1024); } while (0)
; #define PG8_MMA(ai, bj, At, Bt) do { __builtin_amdgcn_s_setprio(1); _Pragma("unroll") for (int m = 0; m < 4; ++m) _Pragma("unroll") for (int n = 0; n < 2; ++n) _Pragma("unroll") for (int k = 0; k < 2; ++k) \
;         acc[ai][bj][m][n] = __builtin_amdgcn_mfma_f32_16x16x32_bf16(Bt[n][k], At[m][k], acc[ai][bj][m][n], 0, 0, 0); __builtin_amdgcn_s_setprio(0); } while (0)
; #define PG8_WAIT_V(n) asm volatile("s_waitcnt vmcnt(" #n ")" ::: "memory")
; #define PG8_WAIT_L(n) asm volatile("s_waitcnt lgkmcnt(" #n ")" ::: "memory")
; #define PG8_BAR __builtin_amdgcn_s_barrier()
; #define PG8_SCHED __builtin_amdgcn_sched_barrier(0)
;     ...
;             PG8_WAIT_V(8); PG8_WAIT_L(0); PG8_BAR; PG8_MMA(1, 0, At, B0); PG8_MMA(1, 1, At, B1); PG8_BAR; PG8_SCHED;
;             PG8_LDB(B0, 1, 0); PG8_LDB(B1, 1, 1); PG8_SCHED; PG8_LDA(At, 1, 0); PG8_STAGE(PG8_SA(0, 1), a2 + hstepA, voffA);
;             PG8_WAIT_V(8); PG8_WAIT_L(0); PG8_BAR; PG8_MMA(0, 0, At, B0); PG8_MMA(0, 1, At, B1); PG8_BAR; PG8_SCHED;
;             PG8_LDA(At, 1, 1); PG8_STAGE(PG8_SB(1, 0), b3, voffB); PG8_STAGE(PG8_SB(1, 1), b3 + hstepB, voffB); PG8_STAGE(PG8_SA(1, 0), a3, voffA);
	s_setprio 1
	s_waitcnt lgkmcnt(0)
	v_mfma_f32_16x16x32_bf16 v[60:63], v[76:79], v[156:159], 0
	v_mfma_f32_16x16x32_bf16 v[56:59], v[100:103], v[156:159], 0
	v_mfma_f32_16x16x32_bf16 v[44:47], v[76:79], v[172:175], 0
	v_mfma_f32_16x16x32_bf16 v[40:43], v[100:103], v[172:175], 0
	v_mfma_f32_16x16x32_bf16 v[28:31], v[76:79], v[180:183], 0
	v_mfma_f32_16x16x32_bf16 v[24:27], v[100:103], v[180:183], 0
	v_mfma_f32_16x16x32_bf16 v[12:15], v[76:79], v[188:191], 0
	v_mfma_f32_16x16x32_bf16 v[8:11], v[100:103], v[188:191], 0
	v_mfma_f32_16x16x32_bf16 v[60:63], v[88:91], v[168:171], v[60:63]
	v_mfma_f32_16x16x32_bf16 v[56:59], v[108:111], v[168:171], v[56:59]
	v_mfma_f32_16x16x32_bf16 v[44:47], v[88:91], v[176:179], v[44:47]
	v_mfma_f32_16x16x32_bf16 v[40:43], v[108:111], v[176:179], v[40:43]
	v_mfma_f32_16x16x32_bf16 v[28:31], v[88:91], v[184:187], v[28:31]
	v_mfma_f32_16x16x32_bf16 v[24:27], v[108:111], v[184:187], v[24:27]
	v_mfma_f32_16x16x32_bf16 v[12:15], v[88:91], v[218:221], v[12:15]
	v_mfma_f32_16x16x32_bf16 v[8:11], v[108:111], v[218:221], v[8:11]
	s_setprio 0
	s_setprio 1
	v_mfma_f32_16x16x32_bf16 v[52:55], v[124:127], v[156:159], 0
	v_mfma_f32_16x16x32_bf16 v[48:51], v[144:147], v[156:159], 0
	v_mfma_f32_16x16x32_bf16 v[36:39], v[124:127], v[172:175], 0
	v_mfma_f32_16x16x32_bf16 v[32:35], v[144:147], v[172:175], 0
	v_mfma_f32_16x16x32_bf16 v[20:23], v[124:127], v[180:183], 0
	v_mfma_f32_16x16x32_bf16 v[16:19], v[144:147], v[180:183], 0
	v_mfma_f32_16x16x32_bf16 v[4:7], v[124:127], v[188:191], 0
	v_mfma_f32_16x16x32_bf16 v[0:3], v[144:147], v[188:191], 0
	v_mfma_f32_16x16x32_bf16 v[52:55], v[128:131], v[168:171], v[52:55]
	v_mfma_f32_16x16x32_bf16 v[48:51], v[152:155], v[168:171], v[48:51]
	v_mfma_f32_16x16x32_bf16 v[36:39], v[128:131], v[176:179], v[36:39]
	v_mfma_f32_16x16x32_bf16 v[32:35], v[152:155], v[176:179], v[32:35]
	v_mfma_f32_16x16x32_bf16 v[20:23], v[128:131], v[184:187], v[20:23]
	v_mfma_f32_16x16x32_bf16 v[16:19], v[152:155], v[184:187], v[16:19]
	v_mfma_f32_16x16x32_bf16 v[4:7], v[128:131], v[218:221], v[4:7]
	s_barrier
	v_mfma_f32_16x16x32_bf16 v[0:3], v[152:155], v[218:221], v[0:3]
	s_setprio 0
	s_add_i32 s69, 0, 0x18000
	s_add_i32 s70, 0, 0x1c000
	v_add_u32_e32 v108, s69, v212
	v_add_u32_e32 v152, s70, v212
	ds_read_b128 v[76:79], v108
	ds_read_b128 v[88:91], v108 offset:1024
	ds_read_b128 v[100:103], v108 offset:2048
	ds_read_b128 v[108:111], v108 offset:3072
	ds_read_b128 v[124:127], v152
	ds_read_b128 v[128:131], v152 offset:1024
	ds_read_b128 v[144:147], v152 offset:2048
	ds_read_b128 v[152:155], v152 offset:3072
	s_add_u32 s20, s20, s24
	s_addc_u32 s21, s21, 0
	s_mov_b32 m0, s45
	v_lshl_add_u64 v[248:249], s[20:21], 0, v[198:199]
	ds_read_b128 v[156:159], v241 offset:32768
	ds_read_b128 v[168:171], v241 offset:33792
	ds_read_b128 v[172:175], v241 offset:34816
	ds_read_b128 v[176:179], v241 offset:35840
	ds_read_b128 v[180:183], v241 offset:36864
	ds_read_b128 v[184:187], v241 offset:37888
	ds_read_b128 v[188:191], v241 offset:38912
	ds_read_b128 v[218:221], v241 offset:39936
	global_load_lds_dwordx4 v[248:249], off
	v_lshl_add_u64 v[248:249], s[20:21], 0, v[194:195]
	s_mov_b32 m0, s46
	s_nop 0
	global_load_lds_dwordx4 v[248:249], off
	s_waitcnt vmcnt(8)
	s_waitcnt lgkmcnt(0)
	s_barrier
	s_setprio 1
	s_waitcnt lgkmcnt(0)
	v_mfma_f32_16x16x32_bf16 v[164:167], v[76:79], v[156:159], v[164:167]
	v_mfma_f32_16x16x32_bf16 v[160:163], v[100:103], v[156:159], v[160:163]
	v_mfma_f32_16x16x32_bf16 v[136:139], v[76:79], v[172:175], v[136:139]
	v_mfma_f32_16x16x32_bf16 v[132:135], v[100:103], v[172:175], v[132:135]
	v_mfma_f32_16x16x32_bf16 v[112:115], v[76:79], v[180:183], v[112:115]
	v_mfma_f32_16x16x32_bf16 v[104:107], v[100:103], v[180:183], v[104:107]
	v_mfma_f32_16x16x32_bf16 v[84:87], v[76:79], v[188:191], v[84:87]
	v_mfma_f32_16x16x32_bf16 v[80:83], v[100:103], v[188:191], v[80:83]
	v_mfma_f32_16x16x32_bf16 v[164:167], v[88:91], v[168:171], v[164:167]
	v_mfma_f32_16x16x32_bf16 v[160:163], v[108:111], v[168:171], v[160:163]
	v_mfma_f32_16x16x32_bf16 v[136:139], v[88:91], v[176:179], v[136:139]
	v_mfma_f32_16x16x32_bf16 v[132:135], v[108:111], v[176:179], v[132:135]
	v_mfma_f32_16x16x32_bf16 v[112:115], v[88:91], v[184:187], v[112:115]
	v_mfma_f32_16x16x32_bf16 v[104:107], v[108:111], v[184:187], v[104:107]
	v_mfma_f32_16x16x32_bf16 v[84:87], v[88:91], v[218:221], v[84:87]
	v_mfma_f32_16x16x32_bf16 v[80:83], v[108:111], v[218:221], v[80:83]
	s_setprio 0
	s_setprio 1
	v_mfma_f32_16x16x32_bf16 v[148:151], v[124:127], v[156:159], v[148:151]
	v_mfma_f32_16x16x32_bf16 v[140:143], v[144:147], v[156:159], v[140:143]
	v_mfma_f32_16x16x32_bf16 v[120:123], v[124:127], v[172:175], v[120:123]
	v_mfma_f32_16x16x32_bf16 v[116:119], v[144:147], v[172:175], v[116:119]
	v_mfma_f32_16x16x32_bf16 v[96:99], v[124:127], v[180:183], v[96:99]
	v_mfma_f32_16x16x32_bf16 v[92:95], v[144:147], v[180:183], v[92:95]
	v_mfma_f32_16x16x32_bf16 v[72:75], v[124:127], v[188:191], v[72:75]
	v_mfma_f32_16x16x32_bf16 v[68:71], v[144:147], v[188:191], v[68:71]
	v_mfma_f32_16x16x32_bf16 v[148:151], v[128:131], v[168:171], v[148:151]
	v_mfma_f32_16x16x32_bf16 v[140:143], v[152:155], v[168:171], v[140:143]
	v_mfma_f32_16x16x32_bf16 v[120:123], v[128:131], v[176:179], v[120:123]
	v_mfma_f32_16x16x32_bf16 v[116:119], v[152:155], v[176:179], v[116:119]
	v_mfma_f32_16x16x32_bf16 v[96:99], v[128:131], v[184:187], v[96:99]
	v_mfma_f32_16x16x32_bf16 v[92:95], v[152:155], v[184:187], v[92:95]
	v_mfma_f32_16x16x32_bf16 v[72:75], v[128:131], v[218:221], v[72:75]
	s_barrier
; #define PG8_STAGE(bufoff, gbase, voff) do { _Pragma("unroll") for (int _i = 0; _i < 2; ++_i) \
;         __builtin_amdgcn_global_load_lds((const unsigned*)((const char*)(gbase) + (voff)[_i]), (PG8_LAS unsigned*)(lds + (bufoff) + ldsw + _i * 8192), 16, 0, 0); } while (0)
; #define PG8_LDA(dst, b, h) do { _Pragma("unroll") for (int m = 0; m < 4; ++m) _Pragma("unroll") for (int k = 0; k < 2; ++k) dst[m][k] = *(const PG8_LAS bf16x8*)(lds + PG8_SA(b, h) + aoff + m * 2048 + k * 1024); } while (0)
; #define PG8_MMA(ai, bj, At, Bt) do { __builtin_amdgcn_s_setprio(1); _Pragma("unroll") for (int m = 0; m < 4; ++m) _Pragma("unroll") for (int n = 0; n < 2; ++n) _Pragma("unroll") for (int k = 0; k < 2; ++k) \
;         acc[ai][bj][m][n] = __builtin_amdgcn_mfma_f32_16x16x32_bf16(Bt[n][k], At[m][k], acc[ai][bj][m][n], 0, 0, 0); __builtin_amdgcn_s_setprio(0); } while (0)
; #define PG8_WAIT_V(n) asm volatile("s_waitcnt vmcnt(" #n ")" ::: "memory")
; #define PG8_WAIT_L(n) asm volatile("s_waitcnt lgkmcnt(" #n ")" ::: "memory")
; #define PG8_BAR __builtin_amdgcn_s_barrier()
; #define PG8_SCHED __builtin_amdgcn_sched_barrier(0)
;     ...
;             PG8_LDA(At, 1, 1); PG8_STAGE(PG8_SB(1, 0), b3, voffB); PG8_STAGE(PG8_SB(1, 1), b3 + hstepB, voffB); PG8_STAGE(PG8_SA(1, 0), a3, voffA);
;             PG8_WAIT_V(8); PG8_WAIT_L(0); PG8_BAR; PG8_MMA(1, 0, At, B0); PG8_MMA(1, 1, At, B1); PG8_BAR; PG8_SCHED;
;         }
	v_mfma_f32_16x16x32_bf16 v[68:71], v[152:155], v[218:221], v[68:71]
	s_setprio 0
	s_add_i32 s20, s69, s25
	v_lshl_add_u64 v[222:223], v[222:223], 0, s[76:77]
	s_mov_b32 m0, s20
	ds_read_b128 v[156:159], v241 offset:49152
	ds_read_b128 v[168:171], v241 offset:50176
	ds_read_b128 v[172:175], v241 offset:51200
	ds_read_b128 v[176:179], v241 offset:52224
	ds_read_b128 v[180:183], v241 offset:53248
	ds_read_b128 v[184:187], v241 offset:54272
	ds_read_b128 v[188:191], v241 offset:55296
	ds_read_b128 v[218:221], v241 offset:56320
	global_load_lds_dwordx4 v[222:223], off
	v_lshl_add_u64 v[222:223], v[224:225], 0, s[76:77]
	s_add_i32 m0, s20, 0x2000
	s_add_i32 s20, s70, s25
	global_load_lds_dwordx4 v[222:223], off
	v_lshl_add_u64 v[222:223], v[244:245], 0, s[76:77]
	s_mov_b32 m0, s20
	s_nop 0
	global_load_lds_dwordx4 v[222:223], off
	v_lshl_add_u64 v[222:223], v[246:247], 0, s[76:77]
	s_add_i32 m0, s20, 0x2000
	s_nop 0
	global_load_lds_dwordx4 v[222:223], off
	v_lshl_add_u64 v[222:223], s[2:3], 0, v[198:199]
	s_mov_b32 m0, s47
	s_nop 0
	global_load_lds_dwordx4 v[222:223], off
	v_lshl_add_u64 v[222:223], s[2:3], 0, v[194:195]
	s_mov_b32 m0, s48
	s_nop 0
	global_load_lds_dwordx4 v[222:223], off
	s_waitcnt vmcnt(8)
	s_waitcnt lgkmcnt(0)
	s_barrier
	s_setprio 1
	s_waitcnt lgkmcnt(0)
	v_mfma_f32_16x16x32_bf16 v[60:63], v[76:79], v[156:159], v[60:63]
	v_mfma_f32_16x16x32_bf16 v[56:59], v[100:103], v[156:159], v[56:59]
	v_mfma_f32_16x16x32_bf16 v[44:47], v[76:79], v[172:175], v[44:47]
	v_mfma_f32_16x16x32_bf16 v[40:43], v[100:103], v[172:175], v[40:43]
	v_mfma_f32_16x16x32_bf16 v[28:31], v[76:79], v[180:183], v[28:31]
	v_mfma_f32_16x16x32_bf16 v[24:27], v[100:103], v[180:183], v[24:27]
	v_mfma_f32_16x16x32_bf16 v[12:15], v[76:79], v[188:191], v[12:15]
	v_mfma_f32_16x16x32_bf16 v[8:11], v[100:103], v[188:191], v[8:11]
	v_mfma_f32_16x16x32_bf16 v[60:63], v[88:91], v[168:171], v[60:63]
	v_mfma_f32_16x16x32_bf16 v[56:59], v[108:111], v[168:171], v[56:59]
	v_mfma_f32_16x16x32_bf16 v[44:47], v[88:91], v[176:179], v[44:47]
	v_mfma_f32_16x16x32_bf16 v[40:43], v[108:111], v[176:179], v[40:43]
	v_mfma_f32_16x16x32_bf16 v[28:31], v[88:91], v[184:187], v[28:31]
	v_mfma_f32_16x16x32_bf16 v[24:27], v[108:111], v[184:187], v[24:27]
	v_mfma_f32_16x16x32_bf16 v[12:15], v[88:91], v[218:221], v[12:15]
	v_mfma_f32_16x16x32_bf16 v[8:11], v[108:111], v[218:221], v[8:11]
	s_setprio 0
	s_setprio 1
	v_mfma_f32_16x16x32_bf16 v[52:55], v[124:127], v[156:159], v[52:55]
	v_mfma_f32_16x16x32_bf16 v[48:51], v[144:147], v[156:159], v[48:51]
	v_mfma_f32_16x16x32_bf16 v[36:39], v[124:127], v[172:175], v[36:39]
	v_mfma_f32_16x16x32_bf16 v[32:35], v[144:147], v[172:175], v[32:35]
	v_mfma_f32_16x16x32_bf16 v[20:23], v[124:127], v[180:183], v[20:23]
	v_mfma_f32_16x16x32_bf16 v[16:19], v[144:147], v[180:183], v[16:19]
	v_mfma_f32_16x16x32_bf16 v[4:7], v[124:127], v[188:191], v[4:7]
	v_mfma_f32_16x16x32_bf16 v[0:3], v[144:147], v[188:191], v[0:3]
	v_mfma_f32_16x16x32_bf16 v[52:55], v[128:131], v[168:171], v[52:55]
	v_mfma_f32_16x16x32_bf16 v[48:51], v[152:155], v[168:171], v[48:51]
	v_mfma_f32_16x16x32_bf16 v[36:39], v[128:131], v[176:179], v[36:39]
	v_mfma_f32_16x16x32_bf16 v[32:35], v[152:155], v[176:179], v[32:35]
	v_mfma_f32_16x16x32_bf16 v[20:23], v[128:131], v[184:187], v[20:23]
	v_mfma_f32_16x16x32_bf16 v[16:19], v[152:155], v[184:187], v[16:19]
	v_mfma_f32_16x16x32_bf16 v[4:7], v[128:131], v[218:221], v[4:7]
	s_barrier
	v_mfma_f32_16x16x32_bf16 v[0:3], v[152:155], v[218:221], v[0:3]
	s_setprio 0
	s_add_u32 s64, s64, 0x100
	s_addc_u32 s65, s65, 0
	s_add_u32 s66, s66, 0x100
	s_addc_u32 s67, s67, 0
	v_lshl_add_u64 v[64:65], v[64:65], 0, s[78:79]
	v_lshl_add_u64 v[66:67], v[66:67], 0, s[78:79]
	s_cmp_ge_u32 s68, s50
	s_mov_b32 s2, s68
	s_cbranch_scc0 .LBB0_534
	s_branch .Lpeel_exit_534
	.p2alignl 6, 3212836864

;     __device__ __forceinline__ const char* tile(const Unit& u, int t) const { return A + (size_t)u.pm * 2 * hstep() + (size_t)t * (BK * 2); }
;     __device__ __forceinline__ const char* tile(const Unit& u, int t) const { return U + (long)(t >> 2) * xoff + (size_t)u.pn * (1024 * 512) + (size_t)u.pm * 2 * hstep() + (size_t)(t & 3) * (BK * 2); }
; #define PG8_STAGE(bufoff, gbase, voff) do { _Pragma("unroll") for (int _i = 0; _i < 2; ++_i) \
;         __builtin_amdgcn_global_load_lds((const unsigned*)((const char*)(gbase) + (voff)[_i]), (PG8_LAS unsigned*)(lds + (bufoff) + ldsw + _i * 8192), 16, 0, 0); } while (0)
; #define PG8_LDA(dst, b, h) do { _Pragma("unroll") for (int m = 0; m < 4; ++m) _Pragma("unroll") for (int k = 0; k < 2; ++k) dst[m][k] = *(const PG8_LAS bf16x8*)(lds + PG8_SA(b, h) + aoff + m * 2048 + k * 1024); } while (0)
; #define PG8_LDB(dst, b, h) do { _Pragma("unroll") for (int n = 0; n < 2; ++n) _Pragma("unroll") for (int k = 0; k < 2; ++k) dst[n][k] = *(const PG8_LAS bf16x8*)(lds + PG8_SB(b, h) + boff + n * 2048 + k * 1024); } while (0)
; #define PG8_MMA(ai, bj, At, Bt) do { __builtin_amdgcn_s_setprio(1); _Pragma("unroll") for (int m = 0; m < 4; ++m) _Pragma("unroll") for (int n = 0; n < 2; ++n) _Pragma("unroll") for (int k = 0; k < 2; ++k) \
;         acc[ai][bj][m][n] = __builtin_amdgcn_mfma_f32_16x16x32_bf16(Bt[n][k], At[m][k], acc[ai][bj][m][n], 0, 0, 0); __builtin_amdgcn_s_setprio(0); } while (0)
; #define PG8_BAR __builtin_amdgcn_s_barrier()
;     ...
;         for (int t = 0; t < nt; t += 2) {
;             const bool last = (t == nt - 2);
;             const char* a1 = AS.tile(cur, t + 1);
;             const char* a2 = last ? AS.tile(nu, 0) : AS.tile(cur, t + 2); const char* b2 = last ? nB : cB + (size_t)(t + 2) * kstep;
;             const char* a3 = last ? AS.tile(nu, 1) : AS.tile(cur, t + 3); const char* b3 = b2 + kstep;
;             PG8_LDB(B0, 0, 0); PG8_LDB(B1, 0, 1); PG8_SCHED; PG8_LDA(At, 0, 0); PG8_STAGE(PG8_SA(1, 1), a1 + hstepA, voffA);
;             PG8_WAIT_V(8); PG8_WAIT_L(0); PG8_BAR; PG8_MMA(0, 0, At, B0); PG8_MMA(0, 1, At, B1); PG8_BAR; PG8_SCHED;
;             PG8_LDA(At, 0, 1); PG8_STAGE(PG8_SB(0, 0), b2, voffB); PG8_STAGE(PG8_SB(0, 1), b2 + hstepB, voffB); PG8_STAGE(PG8_SA(0, 0), a2, voffA);
;             PG8_WAIT_V(8); PG8_WAIT_L(0); PG8_BAR; PG8_MMA(1, 0, At, B0); PG8_MMA(1, 1, At, B1); PG8_BAR; PG8_SCHED;
.Lpeel_702:
	s_add_u32 s20, s40, s2
	s_addc_u32 s21, s41, s3
	s_add_u32 s26, s20, 0x400100
	s_addc_u32 s27, s21, 0
	s_add_u32 s24, s42, s2
	s_addc_u32 s25, s43, s3
	s_add_u32 s20, s20, 0x400180
	s_addc_u32 s21, s21, 0
	s_add_i32 s63, 0, 0x10000
	s_add_i32 s66, 0, 0x14000
	v_add_u32_e32 v156, s63, v185
	v_add_u32_e32 v172, s66, v185
	ds_read_b128 v[132:135], v156
	ds_read_b128 v[136:139], v156 offset:1024
	ds_read_b128 v[140:143], v156 offset:2048
	ds_read_b128 v[156:159], v156 offset:3072
	ds_read_b128 v[160:163], v172
	ds_read_b128 v[164:167], v172 offset:1024
	ds_read_b128 v[168:171], v172 offset:2048
	ds_read_b128 v[172:175], v172 offset:3072
	s_cmpk_eq_i32 s2, 0x700
	s_cselect_b32 s21, s31, s21
	s_cselect_b32 s20, s30, s20
	s_cselect_b32 s25, s28, s25
	s_cselect_b32 s24, s1, s24
	s_cselect_b32 s27, s29, s27
	s_cselect_b32 s26, s19, s26
	v_lshl_add_u64 v[238:239], v[128:129], 0, s[2:3]
	s_add_i32 m0, s49, 0xc000
	ds_read_b128 v[176:179], v190
	ds_read_b128 v[180:183], v190 offset:1024
	ds_read_b128 v[192:195], v190 offset:2048
	ds_read_b128 v[196:199], v190 offset:3072
	ds_read_b128 v[200:203], v190 offset:4096
	ds_read_b128 v[204:207], v190 offset:5120
	ds_read_b128 v[218:221], v190 offset:6144
	ds_read_b128 v[222:225], v190 offset:7168
	global_load_lds_dwordx4 v[238:239], off
	v_lshl_add_u64 v[238:239], v[130:131], 0, s[2:3]
	s_add_i32 m0, s49, 0xe000
	s_nop 0
	global_load_lds_dwordx4 v[238:239], off
	s_waitcnt vmcnt(24)
	s_waitcnt lgkmcnt(0)
	s_barrier
	s_setprio 1
	s_waitcnt lgkmcnt(0)
	v_mfma_f32_16x16x32_bf16 v[124:127], v[132:135], v[176:179], 0
	v_mfma_f32_16x16x32_bf16 v[120:123], v[140:143], v[176:179], 0
	v_mfma_f32_16x16x32_bf16 v[112:115], v[132:135], v[192:195], 0
	v_mfma_f32_16x16x32_bf16 v[104:107], v[140:143], v[192:195], 0
	v_mfma_f32_16x16x32_bf16 v[96:99], v[132:135], v[200:203], 0
	v_mfma_f32_16x16x32_bf16 v[88:91], v[140:143], v[200:203], 0
	v_mfma_f32_16x16x32_bf16 v[80:83], v[132:135], v[218:221], 0
	v_mfma_f32_16x16x32_bf16 v[72:75], v[140:143], v[218:221], 0
	v_mfma_f32_16x16x32_bf16 v[124:127], v[136:139], v[180:183], v[124:127]
	v_mfma_f32_16x16x32_bf16 v[120:123], v[156:159], v[180:183], v[120:123]
	v_mfma_f32_16x16x32_bf16 v[112:115], v[136:139], v[196:199], v[112:115]
	v_mfma_f32_16x16x32_bf16 v[104:107], v[156:159], v[196:199], v[104:107]
	v_mfma_f32_16x16x32_bf16 v[96:99], v[136:139], v[204:207], v[96:99]
	v_mfma_f32_16x16x32_bf16 v[88:91], v[156:159], v[204:207], v[88:91]
	v_mfma_f32_16x16x32_bf16 v[80:83], v[136:139], v[222:225], v[80:83]
	v_mfma_f32_16x16x32_bf16 v[72:75], v[156:159], v[222:225], v[72:75]
	s_setprio 0
	s_setprio 1
	v_mfma_f32_16x16x32_bf16 v[116:119], v[160:163], v[176:179], 0
	v_mfma_f32_16x16x32_bf16 v[108:111], v[168:171], v[176:179], 0
	v_mfma_f32_16x16x32_bf16 v[100:103], v[160:163], v[192:195], 0
	v_mfma_f32_16x16x32_bf16 v[92:95], v[168:171], v[192:195], 0
	v_mfma_f32_16x16x32_bf16 v[84:87], v[160:163], v[200:203], 0
	v_mfma_f32_16x16x32_bf16 v[76:79], v[168:171], v[200:203], 0
	v_mfma_f32_16x16x32_bf16 v[68:71], v[160:163], v[218:221], 0
	v_mfma_f32_16x16x32_bf16 v[64:67], v[168:171], v[218:221], 0
	v_mfma_f32_16x16x32_bf16 v[116:119], v[164:167], v[180:183], v[116:119]
	v_mfma_f32_16x16x32_bf16 v[108:111], v[172:175], v[180:183], v[108:111]
	v_mfma_f32_16x16x32_bf16 v[100:103], v[164:167], v[196:199], v[100:103]
	v_mfma_f32_16x16x32_bf16 v[92:95], v[172:175], v[196:199], v[92:95]
	v_mfma_f32_16x16x32_bf16 v[84:87], v[164:167], v[204:207], v[84:87]
	v_mfma_f32_16x16x32_bf16 v[76:79], v[172:175], v[204:207], v[76:79]
	v_mfma_f32_16x16x32_bf16 v[68:71], v[164:167], v[222:225], v[68:71]
	s_barrier
	v_mfma_f32_16x16x32_bf16 v[64:67], v[172:175], v[222:225], v[64:67]
	s_setprio 0
	s_add_i32 s63, s63, s48
	v_lshl_add_u64 v[238:239], s[24:25], 0, v[148:149]
	s_mov_b32 m0, s63
	ds_read_b128 v[176:179], v190 offset:16384
	ds_read_b128 v[180:183], v190 offset:17408
	ds_read_b128 v[192:195], v190 offset:18432
	ds_read_b128 v[196:199], v190 offset:19456
	ds_read_b128 v[200:203], v190 offset:20480
	ds_read_b128 v[204:207], v190 offset:21504
	ds_read_b128 v[218:221], v190 offset:22528
	ds_read_b128 v[222:225], v190 offset:23552
	global_load_lds_dwordx4 v[238:239], off
	s_add_i32 m0, s63, 0x2000
	s_add_u32 s64, s24, 0x40000
	v_lshl_add_u64 v[240:241], s[24:25], 0, v[144:145]
	s_addc_u32 s65, s25, 0
	s_add_i32 s63, s66, s48
	global_load_lds_dwordx4 v[240:241], off
	v_lshl_add_u64 v[242:243], s[64:65], 0, v[148:149]
	s_mov_b32 m0, s63
	s_nop 0
	global_load_lds_dwordx4 v[242:243], off
	v_lshl_add_u64 v[242:243], s[64:65], 0, v[144:145]
	s_add_i32 m0, s63, 0x2000
	s_nop 0
	global_load_lds_dwordx4 v[242:243], off
	v_lshl_add_u64 v[242:243], s[26:27], 0, v[150:151]
	s_mov_b32 m0, s49
	s_nop 0
	global_load_lds_dwordx4 v[242:243], off
	v_lshl_add_u64 v[242:243], s[26:27], 0, v[146:147]
	s_mov_b32 m0, s50
	s_nop 0
	global_load_lds_dwordx4 v[242:243], off
	s_waitcnt vmcnt(8)
	s_waitcnt lgkmcnt(0)
	s_barrier
; #define PG8_STAGE(bufoff, gbase, voff) do { _Pragma("unroll") for (int _i = 0; _i < 2; ++_i) \
;         __builtin_amdgcn_global_load_lds((const unsigned*)((const char*)(gbase) + (voff)[_i]), (PG8_LAS unsigned*)(lds + (bufoff) + ldsw + _i * 8192), 16, 0, 0); } while (0)
; #define PG8_LDA(dst, b, h) do { _Pragma("unroll") for (int m = 0; m < 4; ++m) _Pragma("unroll") for (int k = 0; k < 2; ++k) dst[m][k] = *(const PG8_LAS bf16x8*)(lds + PG8_SA(b, h) + aoff + m * 2048 + k * 1024); } while (0)
; #define PG8_LDB(dst, b, h) do { _Pragma("unroll") for (int n = 0; n < 2; ++n) _Pragma("unroll") for (int k = 0; k < 2; ++k) dst[n][k] = *(const PG8_LAS bf16x8*)(lds + PG8_SB(b, h) + boff + n * 2048 + k * 1024); } while (0)
; #define PG8_MMA(ai, bj, At, Bt) do { __builtin_amdgcn_s_setprio(1); _Pragma("unroll") for (int m = 0; m < 4; ++m) _Pragma("unroll") for (int n = 0; n < 2; ++n) _Pragma("unroll") for (int k = 0; k < 2; ++k) \
;         acc[ai][bj][m][n] = __builtin_amdgcn_mfma_f32_16x16x32_bf16(Bt[n][k], At[m][k], acc[ai][bj][m][n], 0, 0, 0); __builtin_amdgcn_s_setprio(0); } while (0)
; #define PG8_WAIT_V(n) asm volatile("s_waitcnt vmcnt(" #n ")" ::: "memory")
; #define PG8_WAIT_L(n) asm volatile("s_waitcnt lgkmcnt(" #n ")" ::: "memory")
; #define PG8_BAR __builtin_amdgcn_s_barrier()
; #define PG8_SCHED __builtin_amdgcn_sched_barrier(0)
;     ...
;             PG8_WAIT_V(8); PG8_WAIT_L(0); PG8_BAR; PG8_MMA(1, 0, At, B0); PG8_MMA(1, 1, At, B1); PG8_BAR; PG8_SCHED;
;             PG8_LDB(B0, 1, 0); PG8_LDB(B1, 1, 1); PG8_SCHED; PG8_LDA(At, 1, 0); PG8_STAGE(PG8_SA(0, 1), a2 + hstepA, voffA);
;             PG8_WAIT_V(8); PG8_WAIT_L(0); PG8_BAR; PG8_MMA(0, 0, At, B0); PG8_MMA(0, 1, At, B1); PG8_BAR; PG8_SCHED;
;             PG8_LDA(At, 1, 1); PG8_STAGE(PG8_SB(1, 0), b3, voffB); PG8_STAGE(PG8_SB(1, 1), b3 + hstepB, voffB); PG8_STAGE(PG8_SA(1, 0), a3, voffA);
	s_setprio 1
	s_waitcnt lgkmcnt(0)
	v_mfma_f32_16x16x32_bf16 v[60:63], v[132:135], v[176:179], 0
	v_mfma_f32_16x16x32_bf16 v[56:59], v[140:143], v[176:179], 0
	v_mfma_f32_16x16x32_bf16 v[48:51], v[132:135], v[192:195], 0
	v_mfma_f32_16x16x32_bf16 v[40:43], v[140:143], v[192:195], 0
	v_mfma_f32_16x16x32_bf16 v[32:35], v[132:135], v[200:203], 0
	v_mfma_f32_16x16x32_bf16 v[24:27], v[140:143], v[200:203], 0
	v_mfma_f32_16x16x32_bf16 v[16:19], v[132:135], v[218:221], 0
	v_mfma_f32_16x16x32_bf16 v[8:11], v[140:143], v[218:221], 0
	v_mfma_f32_16x16x32_bf16 v[60:63], v[136:139], v[180:183], v[60:63]
	v_mfma_f32_16x16x32_bf16 v[56:59], v[156:159], v[180:183], v[56:59]
	v_mfma_f32_16x16x32_bf16 v[48:51], v[136:139], v[196:199], v[48:51]
	v_mfma_f32_16x16x32_bf16 v[40:43], v[156:159], v[196:199], v[40:43]
	v_mfma_f32_16x16x32_bf16 v[32:35], v[136:139], v[204:207], v[32:35]
	v_mfma_f32_16x16x32_bf16 v[24:27], v[156:159], v[204:207], v[24:27]
	v_mfma_f32_16x16x32_bf16 v[16:19], v[136:139], v[222:225], v[16:19]
	v_mfma_f32_16x16x32_bf16 v[8:11], v[156:159], v[222:225], v[8:11]
	s_setprio 0
	s_setprio 1
	v_mfma_f32_16x16x32_bf16 v[52:55], v[160:163], v[176:179], 0
	v_mfma_f32_16x16x32_bf16 v[44:47], v[168:171], v[176:179], 0
	v_mfma_f32_16x16x32_bf16 v[36:39], v[160:163], v[192:195], 0
	v_mfma_f32_16x16x32_bf16 v[28:31], v[168:171], v[192:195], 0
	v_mfma_f32_16x16x32_bf16 v[20:23], v[160:163], v[200:203], 0
	v_mfma_f32_16x16x32_bf16 v[12:15], v[168:171], v[200:203], 0
	v_mfma_f32_16x16x32_bf16 v[4:7], v[160:163], v[218:221], 0
	v_mfma_f32_16x16x32_bf16 v[0:3], v[168:171], v[218:221], 0
	v_mfma_f32_16x16x32_bf16 v[52:55], v[164:167], v[180:183], v[52:55]
	v_mfma_f32_16x16x32_bf16 v[44:47], v[172:175], v[180:183], v[44:47]
	v_mfma_f32_16x16x32_bf16 v[36:39], v[164:167], v[196:199], v[36:39]
	v_mfma_f32_16x16x32_bf16 v[28:31], v[172:175], v[196:199], v[28:31]
	v_mfma_f32_16x16x32_bf16 v[20:23], v[164:167], v[204:207], v[20:23]
	v_mfma_f32_16x16x32_bf16 v[12:15], v[172:175], v[204:207], v[12:15]
	v_mfma_f32_16x16x32_bf16 v[4:7], v[164:167], v[222:225], v[4:7]
	s_barrier
	v_mfma_f32_16x16x32_bf16 v[0:3], v[172:175], v[222:225], v[0:3]
	s_setprio 0
	s_add_i32 s63, 0, 0x18000
	s_add_i32 s64, 0, 0x1c000
	v_add_u32_e32 v156, s63, v185
	v_add_u32_e32 v172, s64, v185
	ds_read_b128 v[132:135], v156
	ds_read_b128 v[136:139], v156 offset:1024
	ds_read_b128 v[140:143], v156 offset:2048
	ds_read_b128 v[156:159], v156 offset:3072
	ds_read_b128 v[160:163], v172
	ds_read_b128 v[164:167], v172 offset:1024
	ds_read_b128 v[168:171], v172 offset:2048
	ds_read_b128 v[172:175], v172 offset:3072
	s_add_u32 s26, s26, 0x40000
	s_addc_u32 s27, s27, 0
	s_mov_b32 m0, s51
	v_lshl_add_u64 v[242:243], s[26:27], 0, v[150:151]
	ds_read_b128 v[176:179], v190 offset:32768
	ds_read_b128 v[180:183], v190 offset:33792
	ds_read_b128 v[192:195], v190 offset:34816
	ds_read_b128 v[196:199], v190 offset:35840
	ds_read_b128 v[200:203], v190 offset:36864
	ds_read_b128 v[204:207], v190 offset:37888
	ds_read_b128 v[218:221], v190 offset:38912
	ds_read_b128 v[222:225], v190 offset:39936
	global_load_lds_dwordx4 v[242:243], off
	v_lshl_add_u64 v[242:243], s[26:27], 0, v[146:147]
	s_mov_b32 m0, s52
	s_nop 0
	global_load_lds_dwordx4 v[242:243], off
	s_waitcnt vmcnt(8)
	s_waitcnt lgkmcnt(0)
	s_barrier
	s_setprio 1
	s_waitcnt lgkmcnt(0)
	v_mfma_f32_16x16x32_bf16 v[124:127], v[132:135], v[176:179], v[124:127]
	v_mfma_f32_16x16x32_bf16 v[120:123], v[140:143], v[176:179], v[120:123]
	v_mfma_f32_16x16x32_bf16 v[112:115], v[132:135], v[192:195], v[112:115]
	v_mfma_f32_16x16x32_bf16 v[104:107], v[140:143], v[192:195], v[104:107]
	v_mfma_f32_16x16x32_bf16 v[96:99], v[132:135], v[200:203], v[96:99]
	v_mfma_f32_16x16x32_bf16 v[88:91], v[140:143], v[200:203], v[88:91]
	v_mfma_f32_16x16x32_bf16 v[80:83], v[132:135], v[218:221], v[80:83]
	v_mfma_f32_16x16x32_bf16 v[72:75], v[140:143], v[218:221], v[72:75]
	v_mfma_f32_16x16x32_bf16 v[124:127], v[136:139], v[180:183], v[124:127]
	v_mfma_f32_16x16x32_bf16 v[120:123], v[156:159], v[180:183], v[120:123]
	v_mfma_f32_16x16x32_bf16 v[112:115], v[136:139], v[196:199], v[112:115]
	v_mfma_f32_16x16x32_bf16 v[104:107], v[156:159], v[196:199], v[104:107]
	v_mfma_f32_16x16x32_bf16 v[96:99], v[136:139], v[204:207], v[96:99]
	v_mfma_f32_16x16x32_bf16 v[88:91], v[156:159], v[204:207], v[88:91]
	v_mfma_f32_16x16x32_bf16 v[80:83], v[136:139], v[222:225], v[80:83]
	v_mfma_f32_16x16x32_bf16 v[72:75], v[156:159], v[222:225], v[72:75]
	s_setprio 0
	s_setprio 1
	v_mfma_f32_16x16x32_bf16 v[116:119], v[160:163], v[176:179], v[116:119]
	v_mfma_f32_16x16x32_bf16 v[108:111], v[168:171], v[176:179], v[108:111]
	v_mfma_f32_16x16x32_bf16 v[100:103], v[160:163], v[192:195], v[100:103]
	v_mfma_f32_16x16x32_bf16 v[92:95], v[168:171], v[192:195], v[92:95]
	v_mfma_f32_16x16x32_bf16 v[84:87], v[160:163], v[200:203], v[84:87]
	v_mfma_f32_16x16x32_bf16 v[76:79], v[168:171], v[200:203], v[76:79]
	v_mfma_f32_16x16x32_bf16 v[68:71], v[160:163], v[218:221], v[68:71]
	v_mfma_f32_16x16x32_bf16 v[64:67], v[168:171], v[218:221], v[64:67]
	v_mfma_f32_16x16x32_bf16 v[116:119], v[164:167], v[180:183], v[116:119]
	v_mfma_f32_16x16x32_bf16 v[108:111], v[172:175], v[180:183], v[108:111]
	v_mfma_f32_16x16x32_bf16 v[100:103], v[164:167], v[196:199], v[100:103]
	v_mfma_f32_16x16x32_bf16 v[92:95], v[172:175], v[196:199], v[92:95]
	v_mfma_f32_16x16x32_bf16 v[84:87], v[164:167], v[204:207], v[84:87]
	v_mfma_f32_16x16x32_bf16 v[76:79], v[172:175], v[204:207], v[76:79]
	v_mfma_f32_16x16x32_bf16 v[68:71], v[164:167], v[222:225], v[68:71]
	s_barrier
; #define PG8_STAGE(bufoff, gbase, voff) do { _Pragma("unroll") for (int _i = 0; _i < 2; ++_i) \
;         __builtin_amdgcn_global_load_lds((const unsigned*)((const char*)(gbase) + (voff)[_i]), (PG8_LAS unsigned*)(lds + (bufoff) + ldsw + _i * 8192), 16, 0, 0); } while (0)
; #define PG8_LDA(dst, b, h) do { _Pragma("unroll") for (int m = 0; m < 4; ++m) _Pragma("unroll") for (int k = 0; k < 2; ++k) dst[m][k] = *(const PG8_LAS bf16x8*)(lds + PG8_SA(b, h) + aoff + m * 2048 + k * 1024); } while (0)
; #define PG8_MMA(ai, bj, At, Bt) do { __builtin_amdgcn_s_setprio(1); _Pragma("unroll") for (int m = 0; m < 4; ++m) _Pragma("unroll") for (int n = 0; n < 2; ++n) _Pragma("unroll") for (int k = 0; k < 2; ++k) \
;         acc[ai][bj][m][n] = __builtin_amdgcn_mfma_f32_16x16x32_bf16(Bt[n][k], At[m][k], acc[ai][bj][m][n], 0, 0, 0); __builtin_amdgcn_s_setprio(0); } while (0)
; #define PG8_WAIT_V(n) asm volatile("s_waitcnt vmcnt(" #n ")" ::: "memory")
; #define PG8_WAIT_L(n) asm volatile("s_waitcnt lgkmcnt(" #n ")" ::: "memory")
; #define PG8_BAR __builtin_amdgcn_s_barrier()
; #define PG8_SCHED __builtin_amdgcn_sched_barrier(0)
;     ...
;             PG8_LDA(At, 1, 1); PG8_STAGE(PG8_SB(1, 0), b3, voffB); PG8_STAGE(PG8_SB(1, 1), b3 + hstepB, voffB); PG8_STAGE(PG8_SA(1, 0), a3, voffA);
;             PG8_WAIT_V(8); PG8_WAIT_L(0); PG8_BAR; PG8_MMA(1, 0, At, B0); PG8_MMA(1, 1, At, B1); PG8_BAR; PG8_SCHED;
;         }
	v_mfma_f32_16x16x32_bf16 v[64:67], v[172:175], v[222:225], v[64:67]
	s_setprio 0
	s_add_i32 s26, s63, s48
	v_lshl_add_u64 v[238:239], v[238:239], 0, s[68:69]
	s_mov_b32 m0, s26
	ds_read_b128 v[176:179], v190 offset:49152
	ds_read_b128 v[180:183], v190 offset:50176
	ds_read_b128 v[192:195], v190 offset:51200
	ds_read_b128 v[196:199], v190 offset:52224
	ds_read_b128 v[200:203], v190 offset:53248
	ds_read_b128 v[204:207], v190 offset:54272
	ds_read_b128 v[218:221], v190 offset:55296
	ds_read_b128 v[222:225], v190 offset:56320
	global_load_lds_dwordx4 v[238:239], off
	s_add_i32 m0, s26, 0x2000
	s_add_u32 s24, s24, 0x40080
	v_lshl_add_u64 v[238:239], v[240:241], 0, s[68:69]
	s_addc_u32 s25, s25, 0
	s_add_i32 s26, s64, s48
	global_load_lds_dwordx4 v[238:239], off
	v_lshl_add_u64 v[238:239], s[24:25], 0, v[148:149]
	s_mov_b32 m0, s26
	s_nop 0
	global_load_lds_dwordx4 v[238:239], off
	v_lshl_add_u64 v[238:239], s[24:25], 0, v[144:145]
	s_add_i32 m0, s26, 0x2000
	s_nop 0
	global_load_lds_dwordx4 v[238:239], off
	v_lshl_add_u64 v[238:239], s[20:21], 0, v[150:151]
	s_mov_b32 m0, s53
	s_nop 0
	global_load_lds_dwordx4 v[238:239], off
	v_lshl_add_u64 v[238:239], s[20:21], 0, v[146:147]
	s_mov_b32 m0, s54
	s_nop 0
	global_load_lds_dwordx4 v[238:239], off
	s_waitcnt vmcnt(8)
	s_waitcnt lgkmcnt(0)
	s_barrier
	s_setprio 1
	s_waitcnt lgkmcnt(0)
	v_mfma_f32_16x16x32_bf16 v[60:63], v[132:135], v[176:179], v[60:63]
	v_mfma_f32_16x16x32_bf16 v[56:59], v[140:143], v[176:179], v[56:59]
	v_mfma_f32_16x16x32_bf16 v[48:51], v[132:135], v[192:195], v[48:51]
	v_mfma_f32_16x16x32_bf16 v[40:43], v[140:143], v[192:195], v[40:43]
	v_mfma_f32_16x16x32_bf16 v[32:35], v[132:135], v[200:203], v[32:35]
	v_mfma_f32_16x16x32_bf16 v[24:27], v[140:143], v[200:203], v[24:27]
	v_mfma_f32_16x16x32_bf16 v[16:19], v[132:135], v[218:221], v[16:19]
	v_mfma_f32_16x16x32_bf16 v[8:11], v[140:143], v[218:221], v[8:11]
	v_mfma_f32_16x16x32_bf16 v[60:63], v[136:139], v[180:183], v[60:63]
	v_mfma_f32_16x16x32_bf16 v[56:59], v[156:159], v[180:183], v[56:59]
	v_mfma_f32_16x16x32_bf16 v[48:51], v[136:139], v[196:199], v[48:51]
	v_mfma_f32_16x16x32_bf16 v[40:43], v[156:159], v[196:199], v[40:43]
	v_mfma_f32_16x16x32_bf16 v[32:35], v[136:139], v[204:207], v[32:35]
	v_mfma_f32_16x16x32_bf16 v[24:27], v[156:159], v[204:207], v[24:27]
	v_mfma_f32_16x16x32_bf16 v[16:19], v[136:139], v[222:225], v[16:19]
	v_mfma_f32_16x16x32_bf16 v[8:11], v[156:159], v[222:225], v[8:11]
	s_setprio 0
	s_setprio 1
	v_mfma_f32_16x16x32_bf16 v[52:55], v[160:163], v[176:179], v[52:55]
	v_mfma_f32_16x16x32_bf16 v[44:47], v[168:171], v[176:179], v[44:47]
	v_mfma_f32_16x16x32_bf16 v[36:39], v[160:163], v[192:195], v[36:39]
	v_mfma_f32_16x16x32_bf16 v[28:31], v[168:171], v[192:195], v[28:31]
	v_mfma_f32_16x16x32_bf16 v[20:23], v[160:163], v[200:203], v[20:23]
	v_mfma_f32_16x16x32_bf16 v[12:15], v[168:171], v[200:203], v[12:15]
	v_mfma_f32_16x16x32_bf16 v[4:7], v[160:163], v[218:221], v[4:7]
	v_mfma_f32_16x16x32_bf16 v[0:3], v[168:171], v[218:221], v[0:3]
	v_mfma_f32_16x16x32_bf16 v[52:55], v[164:167], v[180:183], v[52:55]
	v_mfma_f32_16x16x32_bf16 v[44:47], v[172:175], v[180:183], v[44:47]
	v_mfma_f32_16x16x32_bf16 v[36:39], v[164:167], v[196:199], v[36:39]
	v_mfma_f32_16x16x32_bf16 v[28:31], v[172:175], v[196:199], v[28:31]
	v_mfma_f32_16x16x32_bf16 v[20:23], v[164:167], v[204:207], v[20:23]
	v_mfma_f32_16x16x32_bf16 v[12:15], v[172:175], v[204:207], v[12:15]
	v_mfma_f32_16x16x32_bf16 v[4:7], v[164:167], v[222:225], v[4:7]
	s_barrier
	v_mfma_f32_16x16x32_bf16 v[0:3], v[172:175], v[222:225], v[0:3]
	s_setprio 0
	s_add_i32 s62, s62, 2
	s_add_u32 s2, s2, 0x100
	s_addc_u32 s3, s3, 0
	s_cmp_gt_u32 s62, 13
	s_cbranch_scc0 .LBB0_702
	s_branch .Lpeel_exit_702
	.p2alignl 6, 3212836864

;     __device__ __forceinline__ size_t hstep() const { return (size_t)HALF * K * 2; }
;     __device__ __forceinline__ const char* tile(const Unit& u, int t) const { return A + (size_t)u.pm * 2 * hstep() + (size_t)t * (BK * 2); }
;     __device__ __forceinline__ size_t hstep() const { return (size_t)HALF * 512; }
; #define PG8_STAGE(bufoff, gbase, voff) do { _Pragma("unroll") for (int _i = 0; _i < 2; ++_i) \
;         __builtin_amdgcn_global_load_lds((const unsigned*)((const char*)(gbase) + (voff)[_i]), (PG8_LAS unsigned*)(lds + (bufoff) + ldsw + _i * 8192), 16, 0, 0); } while (0)
; #define PG8_LDA(dst, b, h) do { _Pragma("unroll") for (int m = 0; m < 4; ++m) _Pragma("unroll") for (int k = 0; k < 2; ++k) dst[m][k] = *(const PG8_LAS bf16x8*)(lds + PG8_SA(b, h) + aoff + m * 2048 + k * 1024); } while (0)
; #define PG8_LDB(dst, b, h) do { _Pragma("unroll") for (int n = 0; n < 2; ++n) _Pragma("unroll") for (int k = 0; k < 2; ++k) dst[n][k] = *(const PG8_LAS bf16x8*)(lds + PG8_SB(b, h) + boff + n * 2048 + k * 1024); } while (0)
; #define PG8_WAIT_V(n) asm volatile("s_waitcnt vmcnt(" #n ")" ::: "memory")
; #define PG8_WAIT_L(n) asm volatile("s_waitcnt lgkmcnt(" #n ")" ::: "memory")
; #define PG8_BAR __builtin_amdgcn_s_barrier()
; #define PG8_SCHED __builtin_amdgcn_sched_barrier(0)
;     __device__ __forceinline__ const char* tile(const Unit& u, int t) const { return U + (long)(t >> 2) * xoff + (size_t)u.pn * (1024 * 512) + (size_t)u.pm * 2 * hstep() + (size_t)(t & 3) * (BK * 2); }
;     ...
;         for (int t = 0; t < nt; t += 2) {
;             const bool last = (t == nt - 2);
;             const char* a1 = AS.tile(cur, t + 1);
;             const char* a2 = last ? AS.tile(nu, 0) : AS.tile(cur, t + 2); const char* b2 = last ? nB : cB + (size_t)(t + 2) * kstep;
;             const char* a3 = last ? AS.tile(nu, 1) : AS.tile(cur, t + 3); const char* b3 = b2 + kstep;
;             PG8_LDB(B0, 0, 0); PG8_LDB(B1, 0, 1); PG8_SCHED; PG8_LDA(At, 0, 0); PG8_STAGE(PG8_SA(1, 1), a1 + hstepA, voffA);
;             PG8_WAIT_V(8); PG8_WAIT_L(0); PG8_BAR; PG8_MMA(0, 0, At, B0); PG8_MMA(0, 1, At, B1); PG8_BAR; PG8_SCHED;
;             PG8_LDA(At, 0, 1); PG8_STAGE(PG8_SB(0, 0), b2, voffB); PG8_STAGE(PG8_SB(0, 1), b2 + hstepB, voffB); PG8_STAGE(PG8_SA(0, 0), a2, voffA);
;             PG8_WAIT_V(8); PG8_WAIT_L(0); PG8_BAR; PG8_MMA(1, 0, At, B0); PG8_MMA(1, 1, At, B1); PG8_BAR; PG8_SCHED;
.Lpeel_785:
	s_add_u32 s24, s9, s14
	s_addc_u32 s25, s47, 0
	s_xor_b32 s15, s14, 0x100
	s_add_u32 s15, s9, s15
	s_addc_u32 s20, s47, 0
	s_and_b64 s[18:19], s[16:17], exec
	s_cselect_b32 s21, s49, s20
	s_cselect_b32 s20, s48, s15
	s_add_u32 s15, s52, s14
	s_addc_u32 s18, s53, 0
	s_add_u32 s15, s15, 0x100
	s_addc_u32 s22, s18, 0
	s_and_b64 s[18:19], s[16:17], exec
	s_cselect_b32 s23, s46, s22
	s_cselect_b32 s22, s45, s15
	s_addk_i32 s14, 0x180
	s_and_b32 s14, s14, 0x180
	s_add_u32 s18, s9, s14
	s_addc_u32 s19, s47, 0
	s_and_b64 s[14:15], s[16:17], exec
	s_cselect_b32 s14, s50, s18
	s_cselect_b32 s15, s51, s19
	s_add_i32 s17, 0, 0x10000
	s_add_i32 s62, 0, 0x14000
	s_add_u32 s26, s24, 0x10080
	s_addc_u32 s27, s25, 0
	s_add_i32 s61, s17, s30
	s_add_i32 m0, s31, 0xc000
	s_add_i32 s64, s31, 0xe000
	s_add_i32 s58, s61, 0x2000
	v_add_u32_e32 v140, s17, v159
	s_add_u32 s24, s22, 0x10000
	ds_read_b128 v[162:165], v140
	ds_read_b128 v[166:169], v140 offset:1024
	ds_read_b128 v[170:173], v140 offset:2048
	ds_read_b128 v[174:177], v140 offset:3072
	v_add_u32_e32 v140, s62, v159
	s_addc_u32 s25, s23, 0
	s_add_i32 s60, s62, s30
	ds_read_b128 v[178:181], v140
	ds_read_b128 v[182:185], v140 offset:1024
	ds_read_b128 v[186:189], v140 offset:2048
	ds_read_b128 v[190:193], v140 offset:3072
	s_add_i32 s59, s60, 0x2000
	s_add_i32 s57, 0, 0x18000
	s_add_i32 s56, 0, 0x1c000
	s_add_u32 s18, s20, 0x10000
	s_addc_u32 s19, s21, 0
	s_add_i32 s55, s57, s30
	s_add_i32 s54, s55, 0x2000
	s_add_u32 s16, s22, 0x10080
	s_addc_u32 s17, s23, 0
	s_add_i32 s63, s56, s30
	s_add_i32 s62, s63, 0x2000
	v_lshl_add_u64 v[140:141], s[26:27], 0, v[128:129]
	ds_read_b128 v[194:197], v160
	ds_read_b128 v[198:201], v160 offset:1024
	ds_read_b128 v[202:205], v160 offset:2048
	ds_read_b128 v[218:221], v160 offset:3072
	ds_read_b128 v[222:225], v160 offset:4096
	ds_read_b128 v[238:241], v160 offset:5120
	ds_read_b128 v[242:245], v160 offset:6144
	ds_read_b128 v[246:249], v160 offset:7168
	global_load_lds_dwordx4 v[140:141], off
	v_lshl_add_u64 v[140:141], s[26:27], 0, v[130:131]
	s_mov_b32 m0, s64
	s_nop 0
	global_load_lds_dwordx4 v[140:141], off
	s_waitcnt vmcnt(8)
	s_waitcnt lgkmcnt(0)
	s_barrier
	s_setprio 1
	s_waitcnt lgkmcnt(0)
	v_mfma_f32_16x16x32_bf16 v[124:127], v[162:165], v[194:197], 0
	v_mfma_f32_16x16x32_bf16 v[120:123], v[170:173], v[194:197], 0
	v_mfma_f32_16x16x32_bf16 v[116:119], v[162:165], v[202:205], 0
	v_mfma_f32_16x16x32_bf16 v[108:111], v[170:173], v[202:205], 0
	v_mfma_f32_16x16x32_bf16 v[100:103], v[162:165], v[222:225], 0
	v_mfma_f32_16x16x32_bf16 v[92:95], v[170:173], v[222:225], 0
	v_mfma_f32_16x16x32_bf16 v[84:87], v[162:165], v[242:245], 0
	v_mfma_f32_16x16x32_bf16 v[76:79], v[170:173], v[242:245], 0
	v_mfma_f32_16x16x32_bf16 v[124:127], v[166:169], v[198:201], v[124:127]
	v_mfma_f32_16x16x32_bf16 v[120:123], v[174:177], v[198:201], v[120:123]
	v_mfma_f32_16x16x32_bf16 v[116:119], v[166:169], v[218:221], v[116:119]
	v_mfma_f32_16x16x32_bf16 v[108:111], v[174:177], v[218:221], v[108:111]
	v_mfma_f32_16x16x32_bf16 v[100:103], v[166:169], v[238:241], v[100:103]
	v_mfma_f32_16x16x32_bf16 v[92:95], v[174:177], v[238:241], v[92:95]
	v_mfma_f32_16x16x32_bf16 v[84:87], v[166:169], v[246:249], v[84:87]
	v_mfma_f32_16x16x32_bf16 v[76:79], v[174:177], v[246:249], v[76:79]
	s_setprio 0
	s_setprio 1
	v_mfma_f32_16x16x32_bf16 v[112:115], v[178:181], v[194:197], 0
	v_mfma_f32_16x16x32_bf16 v[104:107], v[186:189], v[194:197], 0
	v_mfma_f32_16x16x32_bf16 v[96:99], v[178:181], v[202:205], 0
	v_mfma_f32_16x16x32_bf16 v[88:91], v[186:189], v[202:205], 0
	v_mfma_f32_16x16x32_bf16 v[80:83], v[178:181], v[222:225], 0
	v_mfma_f32_16x16x32_bf16 v[72:75], v[186:189], v[222:225], 0
	v_mfma_f32_16x16x32_bf16 v[68:71], v[178:181], v[242:245], 0
	v_mfma_f32_16x16x32_bf16 v[64:67], v[186:189], v[242:245], 0
	v_mfma_f32_16x16x32_bf16 v[112:115], v[182:185], v[198:201], v[112:115]
	v_mfma_f32_16x16x32_bf16 v[104:107], v[190:193], v[198:201], v[104:107]
	v_mfma_f32_16x16x32_bf16 v[96:99], v[182:185], v[218:221], v[96:99]
	v_mfma_f32_16x16x32_bf16 v[88:91], v[190:193], v[218:221], v[88:91]
	v_mfma_f32_16x16x32_bf16 v[80:83], v[182:185], v[238:241], v[80:83]
	v_mfma_f32_16x16x32_bf16 v[72:75], v[190:193], v[238:241], v[72:75]
	v_mfma_f32_16x16x32_bf16 v[68:71], v[182:185], v[246:249], v[68:71]
	s_barrier
	v_mfma_f32_16x16x32_bf16 v[64:67], v[190:193], v[246:249], v[64:67]
	s_setprio 0
	s_mov_b32 m0, s61
	v_lshl_add_u64 v[140:141], s[22:23], 0, v[134:135]
	ds_read_b128 v[194:197], v160 offset:16384
	ds_read_b128 v[198:201], v160 offset:17408
	ds_read_b128 v[202:205], v160 offset:18432
	ds_read_b128 v[218:221], v160 offset:19456
	ds_read_b128 v[222:225], v160 offset:20480
	ds_read_b128 v[238:241], v160 offset:21504
	ds_read_b128 v[242:245], v160 offset:22528
	ds_read_b128 v[246:249], v160 offset:23552
	global_load_lds_dwordx4 v[140:141], off
	v_lshl_add_u64 v[206:207], s[22:23], 0, v[132:133]
	s_mov_b32 m0, s58
	v_lshl_add_u64 v[250:251], s[24:25], 0, v[134:135]
	global_load_lds_dwordx4 v[206:207], off
	s_mov_b32 m0, s60
	s_nop 0
	global_load_lds_dwordx4 v[250:251], off
	v_lshl_add_u64 v[250:251], s[24:25], 0, v[132:133]
	s_mov_b32 m0, s59
	s_nop 0
	global_load_lds_dwordx4 v[250:251], off
	v_lshl_add_u64 v[250:251], s[20:21], 0, v[128:129]
	s_mov_b32 m0, s31
	s_nop 0
	global_load_lds_dwordx4 v[250:251], off
	v_lshl_add_u64 v[250:251], s[20:21], 0, v[130:131]
	s_mov_b32 m0, s35
	s_nop 0
	global_load_lds_dwordx4 v[250:251], off
	s_waitcnt vmcnt(8)
	s_waitcnt lgkmcnt(0)
	s_barrier
; #define PG8_STAGE(bufoff, gbase, voff) do { _Pragma("unroll") for (int _i = 0; _i < 2; ++_i) \
;         __builtin_amdgcn_global_load_lds((const unsigned*)((const char*)(gbase) + (voff)[_i]), (PG8_LAS unsigned*)(lds + (bufoff) + ldsw + _i * 8192), 16, 0, 0); } while (0)
; #define PG8_LDA(dst, b, h) do { _Pragma("unroll") for (int m = 0; m < 4; ++m) _Pragma("unroll") for (int k = 0; k < 2; ++k) dst[m][k] = *(const PG8_LAS bf16x8*)(lds + PG8_SA(b, h) + aoff + m * 2048 + k * 1024); } while (0)
; #define PG8_LDB(dst, b, h) do { _Pragma("unroll") for (int n = 0; n < 2; ++n) _Pragma("unroll") for (int k = 0; k < 2; ++k) dst[n][k] = *(const PG8_LAS bf16x8*)(lds + PG8_SB(b, h) + boff + n * 2048 + k * 1024); } while (0)
; #define PG8_MMA(ai, bj, At, Bt) do { __builtin_amdgcn_s_setprio(1); _Pragma("unroll") for (int m = 0; m < 4; ++m) _Pragma("unroll") for (int n = 0; n < 2; ++n) _Pragma("unroll") for (int k = 0; k < 2; ++k) \
;         acc[ai][bj][m][n] = __builtin_amdgcn_mfma_f32_16x16x32_bf16(Bt[n][k], At[m][k], acc[ai][bj][m][n], 0, 0, 0); __builtin_amdgcn_s_setprio(0); } while (0)
; #define PG8_WAIT_V(n) asm volatile("s_waitcnt vmcnt(" #n ")" ::: "memory")
; #define PG8_WAIT_L(n) asm volatile("s_waitcnt lgkmcnt(" #n ")" ::: "memory")
; #define PG8_BAR __builtin_amdgcn_s_barrier()
; #define PG8_SCHED __builtin_amdgcn_sched_barrier(0)
;     ...
;             PG8_WAIT_V(8); PG8_WAIT_L(0); PG8_BAR; PG8_MMA(1, 0, At, B0); PG8_MMA(1, 1, At, B1); PG8_BAR; PG8_SCHED;
;             PG8_LDB(B0, 1, 0); PG8_LDB(B1, 1, 1); PG8_SCHED; PG8_LDA(At, 1, 0); PG8_STAGE(PG8_SA(0, 1), a2 + hstepA, voffA);
;             PG8_WAIT_V(8); PG8_WAIT_L(0); PG8_BAR; PG8_MMA(0, 0, At, B0); PG8_MMA(0, 1, At, B1); PG8_BAR; PG8_SCHED;
;             PG8_LDA(At, 1, 1); PG8_STAGE(PG8_SB(1, 0), b3, voffB); PG8_STAGE(PG8_SB(1, 1), b3 + hstepB, voffB); PG8_STAGE(PG8_SA(1, 0), a3, voffA);
	s_setprio 1
	s_waitcnt lgkmcnt(0)
	v_mfma_f32_16x16x32_bf16 v[60:63], v[162:165], v[194:197], 0
	v_mfma_f32_16x16x32_bf16 v[56:59], v[170:173], v[194:197], 0
	v_mfma_f32_16x16x32_bf16 v[52:55], v[162:165], v[202:205], 0
	v_mfma_f32_16x16x32_bf16 v[44:47], v[170:173], v[202:205], 0
	v_mfma_f32_16x16x32_bf16 v[36:39], v[162:165], v[222:225], 0
	v_mfma_f32_16x16x32_bf16 v[28:31], v[170:173], v[222:225], 0
	v_mfma_f32_16x16x32_bf16 v[20:23], v[162:165], v[242:245], 0
	v_mfma_f32_16x16x32_bf16 v[12:15], v[170:173], v[242:245], 0
	v_mfma_f32_16x16x32_bf16 v[60:63], v[166:169], v[198:201], v[60:63]
	v_mfma_f32_16x16x32_bf16 v[56:59], v[174:177], v[198:201], v[56:59]
	v_mfma_f32_16x16x32_bf16 v[52:55], v[166:169], v[218:221], v[52:55]
	v_mfma_f32_16x16x32_bf16 v[44:47], v[174:177], v[218:221], v[44:47]
	v_mfma_f32_16x16x32_bf16 v[36:39], v[166:169], v[238:241], v[36:39]
	v_mfma_f32_16x16x32_bf16 v[28:31], v[174:177], v[238:241], v[28:31]
	v_mfma_f32_16x16x32_bf16 v[20:23], v[166:169], v[246:249], v[20:23]
	v_mfma_f32_16x16x32_bf16 v[12:15], v[174:177], v[246:249], v[12:15]
	s_setprio 0
	s_setprio 1
	v_mfma_f32_16x16x32_bf16 v[48:51], v[178:181], v[194:197], 0
	v_mfma_f32_16x16x32_bf16 v[40:43], v[186:189], v[194:197], 0
	v_mfma_f32_16x16x32_bf16 v[32:35], v[178:181], v[202:205], 0
	v_mfma_f32_16x16x32_bf16 v[24:27], v[186:189], v[202:205], 0
	v_mfma_f32_16x16x32_bf16 v[16:19], v[178:181], v[222:225], 0
	v_mfma_f32_16x16x32_bf16 v[8:11], v[186:189], v[222:225], 0
	v_mfma_f32_16x16x32_bf16 v[4:7], v[178:181], v[242:245], 0
	v_mfma_f32_16x16x32_bf16 v[0:3], v[186:189], v[242:245], 0
	v_mfma_f32_16x16x32_bf16 v[48:51], v[182:185], v[198:201], v[48:51]
	v_mfma_f32_16x16x32_bf16 v[40:43], v[190:193], v[198:201], v[40:43]
	v_mfma_f32_16x16x32_bf16 v[32:35], v[182:185], v[218:221], v[32:35]
	v_mfma_f32_16x16x32_bf16 v[24:27], v[190:193], v[218:221], v[24:27]
	v_mfma_f32_16x16x32_bf16 v[16:19], v[182:185], v[238:241], v[16:19]
	v_mfma_f32_16x16x32_bf16 v[8:11], v[190:193], v[238:241], v[8:11]
	v_mfma_f32_16x16x32_bf16 v[4:7], v[182:185], v[246:249], v[4:7]
	s_barrier
	v_mfma_f32_16x16x32_bf16 v[0:3], v[190:193], v[246:249], v[0:3]
	s_setprio 0
	v_add_u32_e32 v161, s57, v159
	ds_read_b128 v[162:165], v161
	ds_read_b128 v[166:169], v161 offset:1024
	ds_read_b128 v[170:173], v161 offset:2048
	ds_read_b128 v[174:177], v161 offset:3072
	v_add_u32_e32 v161, s56, v159
	ds_read_b128 v[178:181], v161
	ds_read_b128 v[182:185], v161 offset:1024
	ds_read_b128 v[186:189], v161 offset:2048
	ds_read_b128 v[190:193], v161 offset:3072
	s_mov_b32 m0, s36
	v_lshl_add_u64 v[250:251], s[18:19], 0, v[128:129]
	ds_read_b128 v[194:197], v160 offset:32768
	ds_read_b128 v[198:201], v160 offset:33792
	ds_read_b128 v[202:205], v160 offset:34816
	ds_read_b128 v[218:221], v160 offset:35840
	ds_read_b128 v[222:225], v160 offset:36864
	ds_read_b128 v[238:241], v160 offset:37888
	ds_read_b128 v[242:245], v160 offset:38912
	ds_read_b128 v[246:249], v160 offset:39936
	global_load_lds_dwordx4 v[250:251], off
	v_lshl_add_u64 v[250:251], s[18:19], 0, v[130:131]
	s_mov_b32 m0, s37
	s_nop 0
	global_load_lds_dwordx4 v[250:251], off
	s_waitcnt vmcnt(8)
	s_waitcnt lgkmcnt(0)
	s_barrier
	s_setprio 1
	s_waitcnt lgkmcnt(0)
	v_mfma_f32_16x16x32_bf16 v[124:127], v[162:165], v[194:197], v[124:127]
	v_mfma_f32_16x16x32_bf16 v[120:123], v[170:173], v[194:197], v[120:123]
	v_mfma_f32_16x16x32_bf16 v[116:119], v[162:165], v[202:205], v[116:119]
	v_mfma_f32_16x16x32_bf16 v[108:111], v[170:173], v[202:205], v[108:111]
	v_mfma_f32_16x16x32_bf16 v[100:103], v[162:165], v[222:225], v[100:103]
	v_mfma_f32_16x16x32_bf16 v[92:95], v[170:173], v[222:225], v[92:95]
	v_mfma_f32_16x16x32_bf16 v[84:87], v[162:165], v[242:245], v[84:87]
	v_mfma_f32_16x16x32_bf16 v[76:79], v[170:173], v[242:245], v[76:79]
	v_mfma_f32_16x16x32_bf16 v[124:127], v[166:169], v[198:201], v[124:127]
	v_mfma_f32_16x16x32_bf16 v[120:123], v[174:177], v[198:201], v[120:123]
	v_mfma_f32_16x16x32_bf16 v[116:119], v[166:169], v[218:221], v[116:119]
	v_mfma_f32_16x16x32_bf16 v[108:111], v[174:177], v[218:221], v[108:111]
	v_mfma_f32_16x16x32_bf16 v[100:103], v[166:169], v[238:241], v[100:103]
	v_mfma_f32_16x16x32_bf16 v[92:95], v[174:177], v[238:241], v[92:95]
	v_mfma_f32_16x16x32_bf16 v[84:87], v[166:169], v[246:249], v[84:87]
	v_mfma_f32_16x16x32_bf16 v[76:79], v[174:177], v[246:249], v[76:79]
	s_setprio 0
	s_setprio 1
	v_mfma_f32_16x16x32_bf16 v[112:115], v[178:181], v[194:197], v[112:115]
	v_mfma_f32_16x16x32_bf16 v[104:107], v[186:189], v[194:197], v[104:107]
	v_mfma_f32_16x16x32_bf16 v[96:99], v[178:181], v[202:205], v[96:99]
	v_mfma_f32_16x16x32_bf16 v[88:91], v[186:189], v[202:205], v[88:91]
	v_mfma_f32_16x16x32_bf16 v[80:83], v[178:181], v[222:225], v[80:83]
	v_mfma_f32_16x16x32_bf16 v[72:75], v[186:189], v[222:225], v[72:75]
	v_mfma_f32_16x16x32_bf16 v[68:71], v[178:181], v[242:245], v[68:71]
	v_mfma_f32_16x16x32_bf16 v[64:67], v[186:189], v[242:245], v[64:67]
	v_mfma_f32_16x16x32_bf16 v[112:115], v[182:185], v[198:201], v[112:115]
	v_mfma_f32_16x16x32_bf16 v[104:107], v[190:193], v[198:201], v[104:107]
	v_mfma_f32_16x16x32_bf16 v[96:99], v[182:185], v[218:221], v[96:99]
	v_mfma_f32_16x16x32_bf16 v[88:91], v[190:193], v[218:221], v[88:91]
	v_mfma_f32_16x16x32_bf16 v[80:83], v[182:185], v[238:241], v[80:83]
	v_mfma_f32_16x16x32_bf16 v[72:75], v[190:193], v[238:241], v[72:75]
	v_mfma_f32_16x16x32_bf16 v[68:71], v[182:185], v[246:249], v[68:71]
	s_barrier
; #define PG8_STAGE(bufoff, gbase, voff) do { _Pragma("unroll") for (int _i = 0; _i < 2; ++_i) \
;         __builtin_amdgcn_global_load_lds((const unsigned*)((const char*)(gbase) + (voff)[_i]), (PG8_LAS unsigned*)(lds + (bufoff) + ldsw + _i * 8192), 16, 0, 0); } while (0)
; #define PG8_LDA(dst, b, h) do { _Pragma("unroll") for (int m = 0; m < 4; ++m) _Pragma("unroll") for (int k = 0; k < 2; ++k) dst[m][k] = *(const PG8_LAS bf16x8*)(lds + PG8_SA(b, h) + aoff + m * 2048 + k * 1024); } while (0)
; #define PG8_MMA(ai, bj, At, Bt) do { __builtin_amdgcn_s_setprio(1); _Pragma("unroll") for (int m = 0; m < 4; ++m) _Pragma("unroll") for (int n = 0; n < 2; ++n) _Pragma("unroll") for (int k = 0; k < 2; ++k) \
;         acc[ai][bj][m][n] = __builtin_amdgcn_mfma_f32_16x16x32_bf16(Bt[n][k], At[m][k], acc[ai][bj][m][n], 0, 0, 0); __builtin_amdgcn_s_setprio(0); } while (0)
; #define PG8_WAIT_V(n) asm volatile("s_waitcnt vmcnt(" #n ")" ::: "memory")
; #define PG8_WAIT_L(n) asm volatile("s_waitcnt lgkmcnt(" #n ")" ::: "memory")
; #define PG8_BAR __builtin_amdgcn_s_barrier()
; #define PG8_SCHED __builtin_amdgcn_sched_barrier(0)
;     ...
;             PG8_LDA(At, 1, 1); PG8_STAGE(PG8_SB(1, 0), b3, voffB); PG8_STAGE(PG8_SB(1, 1), b3 + hstepB, voffB); PG8_STAGE(PG8_SA(1, 0), a3, voffA);
;             PG8_WAIT_V(8); PG8_WAIT_L(0); PG8_BAR; PG8_MMA(1, 0, At, B0); PG8_MMA(1, 1, At, B1); PG8_BAR; PG8_SCHED;
;         }
	v_mfma_f32_16x16x32_bf16 v[64:67], v[190:193], v[246:249], v[64:67]
	s_setprio 0
	s_mov_b32 m0, s55
	v_lshl_add_u64 v[140:141], v[140:141], 0, s[66:67]
	ds_read_b128 v[194:197], v160 offset:49152
	ds_read_b128 v[198:201], v160 offset:50176
	ds_read_b128 v[202:205], v160 offset:51200
	ds_read_b128 v[218:221], v160 offset:52224
	ds_read_b128 v[222:225], v160 offset:53248
	ds_read_b128 v[238:241], v160 offset:54272
	ds_read_b128 v[242:245], v160 offset:55296
	ds_read_b128 v[246:249], v160 offset:56320
	global_load_lds_dwordx4 v[140:141], off
	v_lshl_add_u64 v[140:141], v[206:207], 0, s[66:67]
	s_mov_b32 m0, s54
	s_nop 0
	global_load_lds_dwordx4 v[140:141], off
	v_lshl_add_u64 v[140:141], s[16:17], 0, v[134:135]
	s_mov_b32 m0, s63
	s_nop 0
	global_load_lds_dwordx4 v[140:141], off
	v_lshl_add_u64 v[140:141], s[16:17], 0, v[132:133]
	s_mov_b32 m0, s62
	s_nop 0
	global_load_lds_dwordx4 v[140:141], off
	v_lshl_add_u64 v[140:141], s[14:15], 0, v[128:129]
	s_mov_b32 m0, s40
	s_nop 0
	global_load_lds_dwordx4 v[140:141], off
	v_lshl_add_u64 v[140:141], s[14:15], 0, v[130:131]
	s_mov_b32 m0, s41
	s_nop 0
	global_load_lds_dwordx4 v[140:141], off
	s_waitcnt vmcnt(8)
	s_waitcnt lgkmcnt(0)
	s_barrier
	s_setprio 1
	s_waitcnt lgkmcnt(0)
	v_mfma_f32_16x16x32_bf16 v[60:63], v[162:165], v[194:197], v[60:63]
	v_mfma_f32_16x16x32_bf16 v[56:59], v[170:173], v[194:197], v[56:59]
	v_mfma_f32_16x16x32_bf16 v[52:55], v[162:165], v[202:205], v[52:55]
	v_mfma_f32_16x16x32_bf16 v[44:47], v[170:173], v[202:205], v[44:47]
	v_mfma_f32_16x16x32_bf16 v[36:39], v[162:165], v[222:225], v[36:39]
	v_mfma_f32_16x16x32_bf16 v[28:31], v[170:173], v[222:225], v[28:31]
	v_mfma_f32_16x16x32_bf16 v[20:23], v[162:165], v[242:245], v[20:23]
	v_mfma_f32_16x16x32_bf16 v[12:15], v[170:173], v[242:245], v[12:15]
	v_mfma_f32_16x16x32_bf16 v[60:63], v[166:169], v[198:201], v[60:63]
	v_mfma_f32_16x16x32_bf16 v[56:59], v[174:177], v[198:201], v[56:59]
	v_mfma_f32_16x16x32_bf16 v[52:55], v[166:169], v[218:221], v[52:55]
	v_mfma_f32_16x16x32_bf16 v[44:47], v[174:177], v[218:221], v[44:47]
	v_mfma_f32_16x16x32_bf16 v[36:39], v[166:169], v[238:241], v[36:39]
	v_mfma_f32_16x16x32_bf16 v[28:31], v[174:177], v[238:241], v[28:31]
	v_mfma_f32_16x16x32_bf16 v[20:23], v[166:169], v[246:249], v[20:23]
	v_mfma_f32_16x16x32_bf16 v[12:15], v[174:177], v[246:249], v[12:15]
	s_setprio 0
	s_setprio 1
	v_mfma_f32_16x16x32_bf16 v[48:51], v[178:181], v[194:197], v[48:51]
	v_mfma_f32_16x16x32_bf16 v[40:43], v[186:189], v[194:197], v[40:43]
	v_mfma_f32_16x16x32_bf16 v[32:35], v[178:181], v[202:205], v[32:35]
	v_mfma_f32_16x16x32_bf16 v[24:27], v[186:189], v[202:205], v[24:27]
	v_mfma_f32_16x16x32_bf16 v[16:19], v[178:181], v[222:225], v[16:19]
	v_mfma_f32_16x16x32_bf16 v[8:11], v[186:189], v[222:225], v[8:11]
	v_mfma_f32_16x16x32_bf16 v[4:7], v[178:181], v[242:245], v[4:7]
	v_mfma_f32_16x16x32_bf16 v[0:3], v[186:189], v[242:245], v[0:3]
	v_mfma_f32_16x16x32_bf16 v[48:51], v[182:185], v[198:201], v[48:51]
	v_mfma_f32_16x16x32_bf16 v[40:43], v[190:193], v[198:201], v[40:43]
	v_mfma_f32_16x16x32_bf16 v[32:35], v[182:185], v[218:221], v[32:35]
	v_mfma_f32_16x16x32_bf16 v[24:27], v[190:193], v[218:221], v[24:27]
	v_mfma_f32_16x16x32_bf16 v[16:19], v[182:185], v[238:241], v[16:19]
	v_mfma_f32_16x16x32_bf16 v[8:11], v[190:193], v[238:241], v[8:11]
	v_mfma_f32_16x16x32_bf16 v[4:7], v[182:185], v[246:249], v[4:7]
	s_barrier
	v_mfma_f32_16x16x32_bf16 v[0:3], v[190:193], v[246:249], v[0:3]
	s_setprio 0
	s_andn2_b64 vcc, exec, s[12:13]
	s_mov_b64 s[16:17], -1
	s_mov_b64 s[12:13], 0
	s_movk_i32 s14, 0x100
	s_cbranch_vccz .LBB0_785
	s_branch .Lpeel_exit_785
	.p2alignl 6, 3212836864
